# v039 + GEMM K-loops: the s_setprio 0/1 flip between the two 16-MFMA blocks of each compute segment deleted (one continuous raise per 32-MFMA segment)
# speedup vs baseline: 1.0019x; 1.0019x over previous
; #define PG8_STAGE(bufoff, gbase, voff) do { _Pragma("unroll") for (int _i = 0; _i < 2; ++_i) \
;         __builtin_amdgcn_global_load_lds((const unsigned*)((const char*)(gbase) + (voff)[_i]), (PG8_LAS unsigned*)(lds + (bufoff) + ldsw + _i * 8192), 16, 0, 0); } while (0)
; #define PG8_LDA(dst, b, h) do { _Pragma("unroll") for (int m = 0; m < 4; ++m) _Pragma("unroll") for (int k = 0; k < 2; ++k) dst[m][k] = *(const PG8_LAS bf16x8*)(lds + PG8_SA(b, h) + aoff + m * 2048 + k * 1024); } while (0)
; #define PG8_LDB(dst, b, h) do { _Pragma("unroll") for (int n = 0; n < 2; ++n) _Pragma("unroll") for (int k = 0; k < 2; ++k) dst[n][k] = *(const PG8_LAS bf16x8*)(lds + PG8_SB(b, h) + boff + n * 2048 + k * 1024); } while (0)
; #define PG8_MMA(ai, bj, At, Bt) do { __builtin_amdgcn_s_setprio(1); _Pragma("unroll") for (int m = 0; m < 4; ++m) _Pragma("unroll") for (int n = 0; n < 2; ++n) _Pragma("unroll") for (int k = 0; k < 2; ++k) \
;         acc[ai][bj][m][n] = __builtin_amdgcn_mfma_f32_16x16x32_bf16(Bt[n][k], At[m][k], acc[ai][bj][m][n], 0, 0, 0); __builtin_amdgcn_s_setprio(0); } while (0)
; #define PG8_WAIT_V(n) asm volatile("s_waitcnt vmcnt(" #n ")" ::: "memory")
; #define PG8_WAIT_L(n) asm volatile("s_waitcnt lgkmcnt(" #n ")" ::: "memory")
; #define PG8_BAR __builtin_amdgcn_s_barrier()
; #define PG8_SCHED __builtin_amdgcn_sched_barrier(0)
; template <class Epi, class Sched, bool ALIGN_EPI = false, bool SP2 = false>
; __device__ __forceinline__ void gemm_phase(PG8_LAS unsigned char* lds, const Gemm g, const Sched& S, const Epi& E) {
;     ...
;             PG8_LDB(B0, 0, 0); PG8_LDB(B1, 0, 1); PG8_SCHED; PG8_LDA(At, 0, 0); PG8_STAGE(PG8_SA(1, 1), a1 + hstep, voffA);
;             PG8_WAIT_V(8); PG8_WAIT_L(0); PG8_BAR; PG8_MMA(0, 0, At, B0); PG8_MMA(0, 1, At, B1); PG8_BAR; PG8_SCHED;
;             PG8_LDA(At, 0, 1); PG8_STAGE(PG8_SB(0, 0), b2, voffB); PG8_STAGE(PG8_SB(0, 1), b2 + hstep, voffB); PG8_STAGE(PG8_SA(0, 0), a2, voffA);
.LBB0_150:
	ds_read_b128 v[154:157], v150
	ds_read_b128 v[158:161], v150 offset:1024
	ds_read_b128 v[162:165], v150 offset:2048
	ds_read_b128 v[172:175], v150 offset:3072
	ds_read_b128 v[176:179], v151
	ds_read_b128 v[180:183], v151 offset:1024
	ds_read_b128 v[184:187], v151 offset:2048
	ds_read_b128 v[188:191], v151 offset:3072
	s_add_u32 s28, s0, 0xfffc0080
	s_addc_u32 s29, s1, -1
	s_cmp_eq_u32 s51, 12
	s_cselect_b32 s31, s21, s29
	s_cselect_b32 s30, s47, s28
	s_cselect_b32 s29, s19, s50
	s_cselect_b32 s28, s48, s49
	v_lshl_add_u64 v[144:145], s[0:1], 0, v[136:137]
	s_add_i32 m0, s27, 0xc000
	ds_read_b128 v[202:205], v152
	ds_read_b128 v[206:209], v152 offset:1024
	ds_read_b128 v[210:213], v152 offset:2048
	ds_read_b128 v[214:217], v152 offset:3072
	ds_read_b128 v[218:221], v152 offset:4096
	ds_read_b128 v[222:225], v152 offset:5120
	ds_read_b128 v[226:229], v152 offset:6144
	ds_read_b128 v[230:233], v152 offset:7168
	global_load_lds_dwordx4 v[144:145], off
	v_lshl_add_u64 v[144:145], s[0:1], 0, v[138:139]
	s_add_i32 m0, s27, 0xe000
	s_nop 0
	global_load_lds_dwordx4 v[144:145], off
	s_waitcnt vmcnt(8)
	s_waitcnt lgkmcnt(0)
	s_barrier
	s_setprio 1
	s_waitcnt lgkmcnt(0)
	v_mfma_f32_16x16x32_bf16 v[124:127], v[154:157], v[202:205], v[124:127]
	v_mfma_f32_16x16x32_bf16 v[120:123], v[162:165], v[202:205], v[120:123]
	v_mfma_f32_16x16x32_bf16 v[108:111], v[154:157], v[210:213], v[108:111]
	v_mfma_f32_16x16x32_bf16 v[104:107], v[162:165], v[210:213], v[104:107]
	v_mfma_f32_16x16x32_bf16 v[92:95], v[154:157], v[218:221], v[92:95]
	v_mfma_f32_16x16x32_bf16 v[88:91], v[162:165], v[218:221], v[88:91]
	v_mfma_f32_16x16x32_bf16 v[76:79], v[154:157], v[226:229], v[76:79]
	v_mfma_f32_16x16x32_bf16 v[72:75], v[162:165], v[226:229], v[72:75]
	v_mfma_f32_16x16x32_bf16 v[124:127], v[158:161], v[206:209], v[124:127]
	v_mfma_f32_16x16x32_bf16 v[120:123], v[172:175], v[206:209], v[120:123]
	v_mfma_f32_16x16x32_bf16 v[108:111], v[158:161], v[214:217], v[108:111]
	v_mfma_f32_16x16x32_bf16 v[104:107], v[172:175], v[214:217], v[104:107]
	v_mfma_f32_16x16x32_bf16 v[92:95], v[158:161], v[222:225], v[92:95]
	v_mfma_f32_16x16x32_bf16 v[88:91], v[172:175], v[222:225], v[88:91]
	v_mfma_f32_16x16x32_bf16 v[76:79], v[158:161], v[230:233], v[76:79]
	v_mfma_f32_16x16x32_bf16 v[72:75], v[172:175], v[230:233], v[72:75]
	v_mfma_f32_16x16x32_bf16 v[116:119], v[176:179], v[202:205], v[116:119]
	v_mfma_f32_16x16x32_bf16 v[112:115], v[184:187], v[202:205], v[112:115]
	v_mfma_f32_16x16x32_bf16 v[100:103], v[176:179], v[210:213], v[100:103]
	v_mfma_f32_16x16x32_bf16 v[96:99], v[184:187], v[210:213], v[96:99]
	v_mfma_f32_16x16x32_bf16 v[84:87], v[176:179], v[218:221], v[84:87]
	v_mfma_f32_16x16x32_bf16 v[80:83], v[184:187], v[218:221], v[80:83]
	v_mfma_f32_16x16x32_bf16 v[68:71], v[176:179], v[226:229], v[68:71]
	v_mfma_f32_16x16x32_bf16 v[64:67], v[184:187], v[226:229], v[64:67]
	v_mfma_f32_16x16x32_bf16 v[116:119], v[180:183], v[206:209], v[116:119]
	v_mfma_f32_16x16x32_bf16 v[112:115], v[188:191], v[206:209], v[112:115]
	v_mfma_f32_16x16x32_bf16 v[100:103], v[180:183], v[214:217], v[100:103]
	v_mfma_f32_16x16x32_bf16 v[96:99], v[188:191], v[214:217], v[96:99]
	v_mfma_f32_16x16x32_bf16 v[84:87], v[180:183], v[222:225], v[84:87]
	v_mfma_f32_16x16x32_bf16 v[80:83], v[188:191], v[222:225], v[80:83]
	v_mfma_f32_16x16x32_bf16 v[68:71], v[180:183], v[230:233], v[68:71]
	v_mfma_f32_16x16x32_bf16 v[64:67], v[188:191], v[230:233], v[64:67]
	s_setprio 0
	s_barrier
	s_add_i32 s52, s44, s34
	v_lshl_add_u64 v[144:145], s[28:29], 0, v[132:133]
	s_mov_b32 m0, s52
	ds_read_b128 v[202:205], v152 offset:16384
	ds_read_b128 v[206:209], v152 offset:17408
	ds_read_b128 v[210:213], v152 offset:18432
	ds_read_b128 v[214:217], v152 offset:19456
	ds_read_b128 v[218:221], v152 offset:20480
	ds_read_b128 v[222:225], v152 offset:21504
	ds_read_b128 v[226:229], v152 offset:22528
	ds_read_b128 v[230:233], v152 offset:23552
	global_load_lds_dwordx4 v[144:145], off
	s_add_i32 m0, s52, 0x2000
	s_add_u32 s52, s28, 0x40000
	v_lshl_add_u64 v[166:167], s[28:29], 0, v[128:129]
	s_addc_u32 s53, s29, 0
	s_add_i32 s54, s45, s34
	global_load_lds_dwordx4 v[166:167], off
	v_lshl_add_u64 v[192:193], s[52:53], 0, v[132:133]
	s_mov_b32 m0, s54
	v_lshl_add_u64 v[196:197], s[30:31], 0, v[130:131]
	global_load_lds_dwordx4 v[192:193], off
	v_lshl_add_u64 v[192:193], s[52:53], 0, v[128:129]
	s_add_i32 m0, s54, 0x2000
	s_nop 0
	global_load_lds_dwordx4 v[192:193], off
	v_lshl_add_u64 v[192:193], s[30:31], 0, v[134:135]
	s_mov_b32 m0, s27
	s_nop 0
	global_load_lds_dwordx4 v[192:193], off
	s_mov_b32 m0, s37
	s_nop 0
	global_load_lds_dwordx4 v[196:197], off
	s_waitcnt vmcnt(8)
	s_waitcnt lgkmcnt(0)
	s_barrier
; #define PG8_STAGE(bufoff, gbase, voff) do { _Pragma("unroll") for (int _i = 0; _i < 2; ++_i) \
;         __builtin_amdgcn_global_load_lds((const unsigned*)((const char*)(gbase) + (voff)[_i]), (PG8_LAS unsigned*)(lds + (bufoff) + ldsw + _i * 8192), 16, 0, 0); } while (0)
; #define PG8_LDA(dst, b, h) do { _Pragma("unroll") for (int m = 0; m < 4; ++m) _Pragma("unroll") for (int k = 0; k < 2; ++k) dst[m][k] = *(const PG8_LAS bf16x8*)(lds + PG8_SA(b, h) + aoff + m * 2048 + k * 1024); } while (0)
; #define PG8_LDB(dst, b, h) do { _Pragma("unroll") for (int n = 0; n < 2; ++n) _Pragma("unroll") for (int k = 0; k < 2; ++k) dst[n][k] = *(const PG8_LAS bf16x8*)(lds + PG8_SB(b, h) + boff + n * 2048 + k * 1024); } while (0)
; #define PG8_MMA(ai, bj, At, Bt) do { __builtin_amdgcn_s_setprio(1); _Pragma("unroll") for (int m = 0; m < 4; ++m) _Pragma("unroll") for (int n = 0; n < 2; ++n) _Pragma("unroll") for (int k = 0; k < 2; ++k) \
;         acc[ai][bj][m][n] = __builtin_amdgcn_mfma_f32_16x16x32_bf16(Bt[n][k], At[m][k], acc[ai][bj][m][n], 0, 0, 0); __builtin_amdgcn_s_setprio(0); } while (0)
; #define PG8_WAIT_V(n) asm volatile("s_waitcnt vmcnt(" #n ")" ::: "memory")
; #define PG8_WAIT_L(n) asm volatile("s_waitcnt lgkmcnt(" #n ")" ::: "memory")
; #define PG8_BAR __builtin_amdgcn_s_barrier()
; #define PG8_SCHED __builtin_amdgcn_sched_barrier(0)
; template <class Epi, class Sched, bool ALIGN_EPI = false, bool SP2 = false>
; __device__ __forceinline__ void gemm_phase(PG8_LAS unsigned char* lds, const Gemm g, const Sched& S, const Epi& E) {
;     ...
;             PG8_WAIT_V(8); PG8_WAIT_L(0); PG8_BAR; PG8_MMA(1, 0, At, B0); PG8_MMA(1, 1, At, B1); PG8_BAR; PG8_SCHED;
;             PG8_LDB(B0, 1, 0); PG8_LDB(B1, 1, 1); PG8_SCHED; PG8_LDA(At, 1, 0); PG8_STAGE(PG8_SA(0, 1), a2 + hstep, voffA);
;             PG8_WAIT_V(8); PG8_WAIT_L(0); PG8_BAR; PG8_MMA(0, 0, At, B0); PG8_MMA(0, 1, At, B1); PG8_BAR; PG8_SCHED;
	s_setprio 1
	s_waitcnt lgkmcnt(0)
	v_mfma_f32_16x16x32_bf16 v[60:63], v[154:157], v[202:205], v[60:63]
	v_mfma_f32_16x16x32_bf16 v[56:59], v[162:165], v[202:205], v[56:59]
	v_mfma_f32_16x16x32_bf16 v[44:47], v[154:157], v[210:213], v[44:47]
	v_mfma_f32_16x16x32_bf16 v[40:43], v[162:165], v[210:213], v[40:43]
	v_mfma_f32_16x16x32_bf16 v[28:31], v[154:157], v[218:221], v[28:31]
	v_mfma_f32_16x16x32_bf16 v[24:27], v[162:165], v[218:221], v[24:27]
	v_mfma_f32_16x16x32_bf16 v[12:15], v[154:157], v[226:229], v[12:15]
	v_mfma_f32_16x16x32_bf16 v[8:11], v[162:165], v[226:229], v[8:11]
	v_mfma_f32_16x16x32_bf16 v[60:63], v[158:161], v[206:209], v[60:63]
	v_mfma_f32_16x16x32_bf16 v[56:59], v[172:175], v[206:209], v[56:59]
	v_mfma_f32_16x16x32_bf16 v[44:47], v[158:161], v[214:217], v[44:47]
	v_mfma_f32_16x16x32_bf16 v[40:43], v[172:175], v[214:217], v[40:43]
	v_mfma_f32_16x16x32_bf16 v[28:31], v[158:161], v[222:225], v[28:31]
	v_mfma_f32_16x16x32_bf16 v[24:27], v[172:175], v[222:225], v[24:27]
	v_mfma_f32_16x16x32_bf16 v[12:15], v[158:161], v[230:233], v[12:15]
	v_mfma_f32_16x16x32_bf16 v[8:11], v[172:175], v[230:233], v[8:11]
	v_mfma_f32_16x16x32_bf16 v[52:55], v[176:179], v[202:205], v[52:55]
	v_mfma_f32_16x16x32_bf16 v[48:51], v[184:187], v[202:205], v[48:51]
	v_mfma_f32_16x16x32_bf16 v[36:39], v[176:179], v[210:213], v[36:39]
	v_mfma_f32_16x16x32_bf16 v[32:35], v[184:187], v[210:213], v[32:35]
	v_mfma_f32_16x16x32_bf16 v[20:23], v[176:179], v[218:221], v[20:23]
	v_mfma_f32_16x16x32_bf16 v[16:19], v[184:187], v[218:221], v[16:19]
	v_mfma_f32_16x16x32_bf16 v[4:7], v[176:179], v[226:229], v[4:7]
	v_mfma_f32_16x16x32_bf16 v[0:3], v[184:187], v[226:229], v[0:3]
	v_mfma_f32_16x16x32_bf16 v[52:55], v[180:183], v[206:209], v[52:55]
	v_mfma_f32_16x16x32_bf16 v[48:51], v[188:191], v[206:209], v[48:51]
	v_mfma_f32_16x16x32_bf16 v[36:39], v[180:183], v[214:217], v[36:39]
	v_mfma_f32_16x16x32_bf16 v[32:35], v[188:191], v[214:217], v[32:35]
	v_mfma_f32_16x16x32_bf16 v[20:23], v[180:183], v[222:225], v[20:23]
	v_mfma_f32_16x16x32_bf16 v[16:19], v[188:191], v[222:225], v[16:19]
	v_mfma_f32_16x16x32_bf16 v[4:7], v[180:183], v[230:233], v[4:7]
	v_mfma_f32_16x16x32_bf16 v[0:3], v[188:191], v[230:233], v[0:3]
	s_setprio 0
	s_barrier
	s_add_i32 s52, 0, 0x18000
	v_add_u32_e32 v153, s52, v147
	s_add_i32 s53, 0, 0x1c000
	ds_read_b128 v[154:157], v153
	ds_read_b128 v[158:161], v153 offset:1024
	ds_read_b128 v[162:165], v153 offset:2048
	ds_read_b128 v[172:175], v153 offset:3072
	v_add_u32_e32 v153, s53, v147
	ds_read_b128 v[176:179], v153
	ds_read_b128 v[180:183], v153 offset:1024
	ds_read_b128 v[184:187], v153 offset:2048
	ds_read_b128 v[188:191], v153 offset:3072
	s_add_u32 s30, s30, 0x40000
	s_addc_u32 s31, s31, 0
	s_mov_b32 m0, s38
	v_lshl_add_u64 v[234:235], s[30:31], 0, v[134:135]
	ds_read_b128 v[202:205], v152 offset:32768
	ds_read_b128 v[206:209], v152 offset:33792
	ds_read_b128 v[210:213], v152 offset:34816
	ds_read_b128 v[214:217], v152 offset:35840
	ds_read_b128 v[218:221], v152 offset:36864
	ds_read_b128 v[222:225], v152 offset:37888
	ds_read_b128 v[226:229], v152 offset:38912
	ds_read_b128 v[230:233], v152 offset:39936
	global_load_lds_dwordx4 v[234:235], off
	v_lshl_add_u64 v[234:235], s[30:31], 0, v[130:131]
	s_mov_b32 m0, s39
	s_nop 0
	global_load_lds_dwordx4 v[234:235], off
	s_waitcnt vmcnt(8)
	s_waitcnt lgkmcnt(0)
	s_barrier
	s_setprio 1
	s_waitcnt lgkmcnt(0)
	v_mfma_f32_16x16x32_bf16 v[124:127], v[154:157], v[202:205], v[124:127]
	v_mfma_f32_16x16x32_bf16 v[120:123], v[162:165], v[202:205], v[120:123]
	v_mfma_f32_16x16x32_bf16 v[108:111], v[154:157], v[210:213], v[108:111]
	v_mfma_f32_16x16x32_bf16 v[104:107], v[162:165], v[210:213], v[104:107]
	v_mfma_f32_16x16x32_bf16 v[92:95], v[154:157], v[218:221], v[92:95]
	v_mfma_f32_16x16x32_bf16 v[88:91], v[162:165], v[218:221], v[88:91]
	v_mfma_f32_16x16x32_bf16 v[76:79], v[154:157], v[226:229], v[76:79]
	v_mfma_f32_16x16x32_bf16 v[72:75], v[162:165], v[226:229], v[72:75]
	v_mfma_f32_16x16x32_bf16 v[124:127], v[158:161], v[206:209], v[124:127]
	v_mfma_f32_16x16x32_bf16 v[120:123], v[172:175], v[206:209], v[120:123]
	v_mfma_f32_16x16x32_bf16 v[108:111], v[158:161], v[214:217], v[108:111]
	v_mfma_f32_16x16x32_bf16 v[104:107], v[172:175], v[214:217], v[104:107]
	v_mfma_f32_16x16x32_bf16 v[92:95], v[158:161], v[222:225], v[92:95]
	v_mfma_f32_16x16x32_bf16 v[88:91], v[172:175], v[222:225], v[88:91]
	v_mfma_f32_16x16x32_bf16 v[76:79], v[158:161], v[230:233], v[76:79]
	v_mfma_f32_16x16x32_bf16 v[72:75], v[172:175], v[230:233], v[72:75]
	v_mfma_f32_16x16x32_bf16 v[116:119], v[176:179], v[202:205], v[116:119]
	v_mfma_f32_16x16x32_bf16 v[112:115], v[184:187], v[202:205], v[112:115]
	v_mfma_f32_16x16x32_bf16 v[100:103], v[176:179], v[210:213], v[100:103]
	v_mfma_f32_16x16x32_bf16 v[96:99], v[184:187], v[210:213], v[96:99]
	v_mfma_f32_16x16x32_bf16 v[84:87], v[176:179], v[218:221], v[84:87]
	v_mfma_f32_16x16x32_bf16 v[80:83], v[184:187], v[218:221], v[80:83]
	v_mfma_f32_16x16x32_bf16 v[68:71], v[176:179], v[226:229], v[68:71]
	v_mfma_f32_16x16x32_bf16 v[64:67], v[184:187], v[226:229], v[64:67]
	v_mfma_f32_16x16x32_bf16 v[116:119], v[180:183], v[206:209], v[116:119]
	v_mfma_f32_16x16x32_bf16 v[112:115], v[188:191], v[206:209], v[112:115]
	v_mfma_f32_16x16x32_bf16 v[100:103], v[180:183], v[214:217], v[100:103]
	v_mfma_f32_16x16x32_bf16 v[96:99], v[188:191], v[214:217], v[96:99]
	v_mfma_f32_16x16x32_bf16 v[84:87], v[180:183], v[222:225], v[84:87]
	v_mfma_f32_16x16x32_bf16 v[80:83], v[188:191], v[222:225], v[80:83]
	v_mfma_f32_16x16x32_bf16 v[68:71], v[180:183], v[230:233], v[68:71]
	v_mfma_f32_16x16x32_bf16 v[64:67], v[188:191], v[230:233], v[64:67]
	s_setprio 0
	s_barrier
; #define PG8_STAGE(bufoff, gbase, voff) do { _Pragma("unroll") for (int _i = 0; _i < 2; ++_i) \
;         __builtin_amdgcn_global_load_lds((const unsigned*)((const char*)(gbase) + (voff)[_i]), (PG8_LAS unsigned*)(lds + (bufoff) + ldsw + _i * 8192), 16, 0, 0); } while (0)
; #define PG8_LDA(dst, b, h) do { _Pragma("unroll") for (int m = 0; m < 4; ++m) _Pragma("unroll") for (int k = 0; k < 2; ++k) dst[m][k] = *(const PG8_LAS bf16x8*)(lds + PG8_SA(b, h) + aoff + m * 2048 + k * 1024); } while (0)
; #define PG8_MMA(ai, bj, At, Bt) do { __builtin_amdgcn_s_setprio(1); _Pragma("unroll") for (int m = 0; m < 4; ++m) _Pragma("unroll") for (int n = 0; n < 2; ++n) _Pragma("unroll") for (int k = 0; k < 2; ++k) \
;         acc[ai][bj][m][n] = __builtin_amdgcn_mfma_f32_16x16x32_bf16(Bt[n][k], At[m][k], acc[ai][bj][m][n], 0, 0, 0); __builtin_amdgcn_s_setprio(0); } while (0)
; #define PG8_WAIT_V(n) asm volatile("s_waitcnt vmcnt(" #n ")" ::: "memory")
; #define PG8_WAIT_L(n) asm volatile("s_waitcnt lgkmcnt(" #n ")" ::: "memory")
; #define PG8_BAR __builtin_amdgcn_s_barrier()
; #define PG8_SCHED __builtin_amdgcn_sched_barrier(0)
; template <class Epi, class Sched, bool ALIGN_EPI = false, bool SP2 = false>
; __device__ __forceinline__ void gemm_phase(PG8_LAS unsigned char* lds, const Gemm g, const Sched& S, const Epi& E) {
;     ...
;         for (int t = 0; t < nt; t += 2) {
;             const bool last = (t == nt - 2);
;     ...
;             PG8_LDA(At, 1, 1); PG8_STAGE(PG8_SB(1, 0), b3, voffB); PG8_STAGE(PG8_SB(1, 1), b3 + hstep, voffB); PG8_STAGE(PG8_SA(1, 0), a3, voffA);
;             PG8_WAIT_V(8); PG8_WAIT_L(0); PG8_BAR; PG8_MMA(1, 0, At, B0); PG8_MMA(1, 1, At, B1); PG8_BAR; PG8_SCHED;
	s_add_i32 s30, s52, s34
	v_lshl_add_u64 v[144:145], v[144:145], 0, s[10:11]
	s_mov_b32 m0, s30
	ds_read_b128 v[202:205], v152 offset:49152
	ds_read_b128 v[206:209], v152 offset:50176
	ds_read_b128 v[210:213], v152 offset:51200
	ds_read_b128 v[214:217], v152 offset:52224
	ds_read_b128 v[218:221], v152 offset:53248
	ds_read_b128 v[222:225], v152 offset:54272
	ds_read_b128 v[226:229], v152 offset:55296
	ds_read_b128 v[230:233], v152 offset:56320
	global_load_lds_dwordx4 v[144:145], off
	s_add_i32 m0, s30, 0x2000
	s_add_u32 s28, s28, 0x40080
	v_lshl_add_u64 v[144:145], v[166:167], 0, s[10:11]
	s_addc_u32 s29, s29, 0
	s_add_i32 s30, s53, s34
	global_load_lds_dwordx4 v[144:145], off
	v_lshl_add_u64 v[144:145], s[28:29], 0, v[132:133]
	s_mov_b32 m0, s30
	s_nop 0
	global_load_lds_dwordx4 v[144:145], off
	v_lshl_add_u64 v[144:145], s[28:29], 0, v[128:129]
	s_add_i32 m0, s30, 0x2000
	s_nop 0
	global_load_lds_dwordx4 v[144:145], off
	v_lshl_add_u64 v[144:145], v[192:193], 0, s[10:11]
	s_mov_b32 m0, s41
	s_nop 0
	global_load_lds_dwordx4 v[144:145], off
	v_lshl_add_u64 v[144:145], v[196:197], 0, s[10:11]
	s_mov_b32 m0, s42
	s_nop 0
	global_load_lds_dwordx4 v[144:145], off
	s_waitcnt vmcnt(8)
	s_waitcnt lgkmcnt(0)
	s_barrier
	s_setprio 1
	s_waitcnt lgkmcnt(0)
	v_mfma_f32_16x16x32_bf16 v[60:63], v[154:157], v[202:205], v[60:63]
	v_mfma_f32_16x16x32_bf16 v[56:59], v[162:165], v[202:205], v[56:59]
	v_mfma_f32_16x16x32_bf16 v[44:47], v[154:157], v[210:213], v[44:47]
	v_mfma_f32_16x16x32_bf16 v[40:43], v[162:165], v[210:213], v[40:43]
	v_mfma_f32_16x16x32_bf16 v[28:31], v[154:157], v[218:221], v[28:31]
	v_mfma_f32_16x16x32_bf16 v[24:27], v[162:165], v[218:221], v[24:27]
	v_mfma_f32_16x16x32_bf16 v[12:15], v[154:157], v[226:229], v[12:15]
	v_mfma_f32_16x16x32_bf16 v[8:11], v[162:165], v[226:229], v[8:11]
	v_mfma_f32_16x16x32_bf16 v[60:63], v[158:161], v[206:209], v[60:63]
	v_mfma_f32_16x16x32_bf16 v[56:59], v[172:175], v[206:209], v[56:59]
	v_mfma_f32_16x16x32_bf16 v[44:47], v[158:161], v[214:217], v[44:47]
	v_mfma_f32_16x16x32_bf16 v[40:43], v[172:175], v[214:217], v[40:43]
	v_mfma_f32_16x16x32_bf16 v[28:31], v[158:161], v[222:225], v[28:31]
	v_mfma_f32_16x16x32_bf16 v[24:27], v[172:175], v[222:225], v[24:27]
	v_mfma_f32_16x16x32_bf16 v[12:15], v[158:161], v[230:233], v[12:15]
	v_mfma_f32_16x16x32_bf16 v[8:11], v[172:175], v[230:233], v[8:11]
	v_mfma_f32_16x16x32_bf16 v[52:55], v[176:179], v[202:205], v[52:55]
	v_mfma_f32_16x16x32_bf16 v[48:51], v[184:187], v[202:205], v[48:51]
	v_mfma_f32_16x16x32_bf16 v[36:39], v[176:179], v[210:213], v[36:39]
	v_mfma_f32_16x16x32_bf16 v[32:35], v[184:187], v[210:213], v[32:35]
	v_mfma_f32_16x16x32_bf16 v[20:23], v[176:179], v[218:221], v[20:23]
	v_mfma_f32_16x16x32_bf16 v[16:19], v[184:187], v[218:221], v[16:19]
	v_mfma_f32_16x16x32_bf16 v[4:7], v[176:179], v[226:229], v[4:7]
	v_mfma_f32_16x16x32_bf16 v[0:3], v[184:187], v[226:229], v[0:3]
	v_mfma_f32_16x16x32_bf16 v[52:55], v[180:183], v[206:209], v[52:55]
	v_mfma_f32_16x16x32_bf16 v[48:51], v[188:191], v[206:209], v[48:51]
	v_mfma_f32_16x16x32_bf16 v[36:39], v[180:183], v[214:217], v[36:39]
	v_mfma_f32_16x16x32_bf16 v[32:35], v[188:191], v[214:217], v[32:35]
	v_mfma_f32_16x16x32_bf16 v[20:23], v[180:183], v[222:225], v[20:23]
	v_mfma_f32_16x16x32_bf16 v[16:19], v[188:191], v[222:225], v[16:19]
	v_mfma_f32_16x16x32_bf16 v[4:7], v[180:183], v[230:233], v[4:7]
	v_mfma_f32_16x16x32_bf16 v[0:3], v[188:191], v[230:233], v[0:3]
	s_setprio 0
	s_barrier
	s_add_i32 s51, s51, 2
	s_add_u32 s0, s0, 0x100
	s_addc_u32 s1, s1, 0
	s_add_u32 s49, s49, 0x100
	s_addc_u32 s50, s50, 0
	s_cmp_gt_u32 s51, 13
	s_cbranch_scc0 .LBB0_150
	s_and_b64 vcc, exec, s[12:13]
	s_cbranch_vccz .LBB0_153
	s_barrier

; #define PG8_STAGE(bufoff, gbase, voff) do { _Pragma("unroll") for (int _i = 0; _i < 2; ++_i) \
;         __builtin_amdgcn_global_load_lds((const unsigned*)((const char*)(gbase) + (voff)[_i]), (PG8_LAS unsigned*)(lds + (bufoff) + ldsw + _i * 8192), 16, 0, 0); } while (0)
; #define PG8_LDA(dst, b, h) do { _Pragma("unroll") for (int m = 0; m < 4; ++m) _Pragma("unroll") for (int k = 0; k < 2; ++k) dst[m][k] = *(const PG8_LAS bf16x8*)(lds + PG8_SA(b, h) + aoff + m * 2048 + k * 1024); } while (0)
; #define PG8_LDB(dst, b, h) do { _Pragma("unroll") for (int n = 0; n < 2; ++n) _Pragma("unroll") for (int k = 0; k < 2; ++k) dst[n][k] = *(const PG8_LAS bf16x8*)(lds + PG8_SB(b, h) + boff + n * 2048 + k * 1024); } while (0)
; #define PG8_MMA(ai, bj, At, Bt) do { __builtin_amdgcn_s_setprio(1); _Pragma("unroll") for (int m = 0; m < 4; ++m) _Pragma("unroll") for (int n = 0; n < 2; ++n) _Pragma("unroll") for (int k = 0; k < 2; ++k) \
;         acc[ai][bj][m][n] = __builtin_amdgcn_mfma_f32_16x16x32_bf16(Bt[n][k], At[m][k], acc[ai][bj][m][n], 0, 0, 0); __builtin_amdgcn_s_setprio(0); } while (0)
; #define PG8_WAIT_V(n) asm volatile("s_waitcnt vmcnt(" #n ")" ::: "memory")
; #define PG8_WAIT_L(n) asm volatile("s_waitcnt lgkmcnt(" #n ")" ::: "memory")
; #define PG8_BAR __builtin_amdgcn_s_barrier()
; #define PG8_SCHED __builtin_amdgcn_sched_barrier(0)
; template <class Epi, class Sched, bool ALIGN_EPI = false, bool SP2 = false>
; __device__ __forceinline__ void gemm_phase(PG8_LAS unsigned char* lds, const Gemm g, const Sched& S, const Epi& E) {
;     ...
;             PG8_LDB(B0, 0, 0); PG8_LDB(B1, 0, 1); PG8_SCHED; PG8_LDA(At, 0, 0); PG8_STAGE(PG8_SA(1, 1), a1 + hstep, voffA);
;             PG8_WAIT_V(8); PG8_WAIT_L(0); PG8_BAR; PG8_MMA(0, 0, At, B0); PG8_MMA(0, 1, At, B1); PG8_BAR; PG8_SCHED;
;             PG8_LDA(At, 0, 1); PG8_STAGE(PG8_SB(0, 0), b2, voffB); PG8_STAGE(PG8_SB(0, 1), b2 + hstep, voffB); PG8_STAGE(PG8_SA(0, 0), a2, voffA);
.LBB0_232:
	ds_read_b128 v[128:131], v218
	ds_read_b128 v[132:135], v218 offset:1024
	ds_read_b128 v[136:139], v218 offset:2048
	ds_read_b128 v[140:143], v218 offset:3072
	ds_read_b128 v[144:147], v219
	ds_read_b128 v[148:151], v219 offset:1024
	ds_read_b128 v[152:155], v219 offset:2048
	ds_read_b128 v[156:159], v219 offset:3072
	s_add_u32 s30, s0, 0x100
	s_addc_u32 s31, s1, 0
	s_cmp_eq_u32 s55, 40
	s_cselect_b32 s37, s13, s31
	s_cselect_b32 s36, s12, s30
	s_cselect_b32 s35, s29, s54
	s_cselect_b32 s34, s28, s33
	v_lshl_add_u64 v[192:193], s[0:1], 0, v[182:183]
	s_add_i32 m0, s39, 0xc000
	ds_read_b128 v[160:163], v220
	ds_read_b128 v[164:167], v220 offset:1024
	ds_read_b128 v[188:191], v220 offset:2048
	ds_read_b128 v[226:229], v220 offset:3072
	ds_read_b128 v[230:233], v220 offset:4096
	ds_read_b128 v[234:237], v220 offset:5120
	ds_read_b128 v[238:241], v220 offset:6144
	ds_read_b128 v[242:245], v220 offset:7168
	global_load_lds_dwordx4 v[192:193], off
	v_lshl_add_u64 v[192:193], s[0:1], 0, v[184:185]
	s_add_i32 m0, s39, 0xe000
	s_nop 0
	global_load_lds_dwordx4 v[192:193], off
	s_waitcnt vmcnt(8)
	s_waitcnt lgkmcnt(0)
	s_barrier
	s_setprio 1
	s_waitcnt lgkmcnt(0)
	v_mfma_f32_16x16x32_bf16 v[124:127], v[128:131], v[160:163], v[124:127]
	v_mfma_f32_16x16x32_bf16 v[120:123], v[136:139], v[160:163], v[120:123]
	v_mfma_f32_16x16x32_bf16 v[108:111], v[128:131], v[188:191], v[108:111]
	v_mfma_f32_16x16x32_bf16 v[104:107], v[136:139], v[188:191], v[104:107]
	v_mfma_f32_16x16x32_bf16 v[92:95], v[128:131], v[230:233], v[92:95]
	v_mfma_f32_16x16x32_bf16 v[88:91], v[136:139], v[230:233], v[88:91]
	v_mfma_f32_16x16x32_bf16 v[76:79], v[128:131], v[238:241], v[76:79]
	v_mfma_f32_16x16x32_bf16 v[72:75], v[136:139], v[238:241], v[72:75]
	v_mfma_f32_16x16x32_bf16 v[124:127], v[132:135], v[164:167], v[124:127]
	v_mfma_f32_16x16x32_bf16 v[120:123], v[140:143], v[164:167], v[120:123]
	v_mfma_f32_16x16x32_bf16 v[108:111], v[132:135], v[226:229], v[108:111]
	v_mfma_f32_16x16x32_bf16 v[104:107], v[140:143], v[226:229], v[104:107]
	v_mfma_f32_16x16x32_bf16 v[92:95], v[132:135], v[234:237], v[92:95]
	v_mfma_f32_16x16x32_bf16 v[88:91], v[140:143], v[234:237], v[88:91]
	v_mfma_f32_16x16x32_bf16 v[76:79], v[132:135], v[242:245], v[76:79]
	v_mfma_f32_16x16x32_bf16 v[72:75], v[140:143], v[242:245], v[72:75]
	v_mfma_f32_16x16x32_bf16 v[116:119], v[144:147], v[160:163], v[116:119]
	v_mfma_f32_16x16x32_bf16 v[112:115], v[152:155], v[160:163], v[112:115]
	v_mfma_f32_16x16x32_bf16 v[100:103], v[144:147], v[188:191], v[100:103]
	v_mfma_f32_16x16x32_bf16 v[96:99], v[152:155], v[188:191], v[96:99]
	v_mfma_f32_16x16x32_bf16 v[84:87], v[144:147], v[230:233], v[84:87]
	v_mfma_f32_16x16x32_bf16 v[80:83], v[152:155], v[230:233], v[80:83]
	v_mfma_f32_16x16x32_bf16 v[68:71], v[144:147], v[238:241], v[68:71]
	v_mfma_f32_16x16x32_bf16 v[64:67], v[152:155], v[238:241], v[64:67]
	v_mfma_f32_16x16x32_bf16 v[116:119], v[148:151], v[164:167], v[116:119]
	v_mfma_f32_16x16x32_bf16 v[112:115], v[156:159], v[164:167], v[112:115]
	v_mfma_f32_16x16x32_bf16 v[100:103], v[148:151], v[226:229], v[100:103]
	v_mfma_f32_16x16x32_bf16 v[96:99], v[156:159], v[226:229], v[96:99]
	v_mfma_f32_16x16x32_bf16 v[84:87], v[148:151], v[234:237], v[84:87]
	v_mfma_f32_16x16x32_bf16 v[80:83], v[156:159], v[234:237], v[80:83]
	v_mfma_f32_16x16x32_bf16 v[68:71], v[148:151], v[242:245], v[68:71]
	v_mfma_f32_16x16x32_bf16 v[64:67], v[156:159], v[242:245], v[64:67]
	s_setprio 0
	s_barrier
	s_add_i32 s0, s48, s38
	v_lshl_add_u64 v[192:193], s[34:35], 0, v[174:175]
	s_mov_b32 m0, s0
	ds_read_b128 v[160:163], v220 offset:16384
	ds_read_b128 v[164:167], v220 offset:17408
	ds_read_b128 v[188:191], v220 offset:18432
	ds_read_b128 v[226:229], v220 offset:19456
	ds_read_b128 v[230:233], v220 offset:20480
	ds_read_b128 v[234:237], v220 offset:21504
	ds_read_b128 v[238:241], v220 offset:22528
	ds_read_b128 v[242:245], v220 offset:23552
	global_load_lds_dwordx4 v[192:193], off
	s_add_i32 m0, s0, 0x2000
	s_add_u32 s0, s34, 0xb0000
	v_lshl_add_u64 v[246:247], s[34:35], 0, v[178:179]
	s_addc_u32 s1, s35, 0
	s_add_i32 s56, s49, s38
	global_load_lds_dwordx4 v[246:247], off
	v_lshl_add_u64 v[248:249], s[0:1], 0, v[174:175]
	s_mov_b32 m0, s56
	v_lshl_add_u64 v[250:251], s[36:37], 0, v[176:177]
	global_load_lds_dwordx4 v[248:249], off
	v_lshl_add_u64 v[248:249], s[0:1], 0, v[178:179]
	s_add_i32 m0, s56, 0x2000
	s_nop 0
	global_load_lds_dwordx4 v[248:249], off
	v_lshl_add_u64 v[248:249], s[36:37], 0, v[172:173]
	s_mov_b32 m0, s39
	s_nop 0
	global_load_lds_dwordx4 v[248:249], off
	s_mov_b32 m0, s40
	s_nop 0
	global_load_lds_dwordx4 v[250:251], off
	s_waitcnt vmcnt(8)
	s_waitcnt lgkmcnt(0)
	s_barrier
; #define PG8_STAGE(bufoff, gbase, voff) do { _Pragma("unroll") for (int _i = 0; _i < 2; ++_i) \
;         __builtin_amdgcn_global_load_lds((const unsigned*)((const char*)(gbase) + (voff)[_i]), (PG8_LAS unsigned*)(lds + (bufoff) + ldsw + _i * 8192), 16, 0, 0); } while (0)
; #define PG8_LDA(dst, b, h) do { _Pragma("unroll") for (int m = 0; m < 4; ++m) _Pragma("unroll") for (int k = 0; k < 2; ++k) dst[m][k] = *(const PG8_LAS bf16x8*)(lds + PG8_SA(b, h) + aoff + m * 2048 + k * 1024); } while (0)
; #define PG8_LDB(dst, b, h) do { _Pragma("unroll") for (int n = 0; n < 2; ++n) _Pragma("unroll") for (int k = 0; k < 2; ++k) dst[n][k] = *(const PG8_LAS bf16x8*)(lds + PG8_SB(b, h) + boff + n * 2048 + k * 1024); } while (0)
; #define PG8_MMA(ai, bj, At, Bt) do { __builtin_amdgcn_s_setprio(1); _Pragma("unroll") for (int m = 0; m < 4; ++m) _Pragma("unroll") for (int n = 0; n < 2; ++n) _Pragma("unroll") for (int k = 0; k < 2; ++k) \
;         acc[ai][bj][m][n] = __builtin_amdgcn_mfma_f32_16x16x32_bf16(Bt[n][k], At[m][k], acc[ai][bj][m][n], 0, 0, 0); __builtin_amdgcn_s_setprio(0); } while (0)
; #define PG8_WAIT_V(n) asm volatile("s_waitcnt vmcnt(" #n ")" ::: "memory")
; #define PG8_WAIT_L(n) asm volatile("s_waitcnt lgkmcnt(" #n ")" ::: "memory")
; #define PG8_BAR __builtin_amdgcn_s_barrier()
; #define PG8_SCHED __builtin_amdgcn_sched_barrier(0)
; template <class Epi, class Sched, bool ALIGN_EPI = false, bool SP2 = false>
; __device__ __forceinline__ void gemm_phase(PG8_LAS unsigned char* lds, const Gemm g, const Sched& S, const Epi& E) {
;     ...
;             PG8_WAIT_V(8); PG8_WAIT_L(0); PG8_BAR; PG8_MMA(1, 0, At, B0); PG8_MMA(1, 1, At, B1); PG8_BAR; PG8_SCHED;
;             PG8_LDB(B0, 1, 0); PG8_LDB(B1, 1, 1); PG8_SCHED; PG8_LDA(At, 1, 0); PG8_STAGE(PG8_SA(0, 1), a2 + hstep, voffA);
;             PG8_WAIT_V(8); PG8_WAIT_L(0); PG8_BAR; PG8_MMA(0, 0, At, B0); PG8_MMA(0, 1, At, B1); PG8_BAR; PG8_SCHED;
	s_setprio 1
	s_waitcnt lgkmcnt(0)
	v_mfma_f32_16x16x32_bf16 v[60:63], v[128:131], v[160:163], v[60:63]
	v_mfma_f32_16x16x32_bf16 v[56:59], v[136:139], v[160:163], v[56:59]
	v_mfma_f32_16x16x32_bf16 v[44:47], v[128:131], v[188:191], v[44:47]
	v_mfma_f32_16x16x32_bf16 v[40:43], v[136:139], v[188:191], v[40:43]
	v_mfma_f32_16x16x32_bf16 v[28:31], v[128:131], v[230:233], v[28:31]
	v_mfma_f32_16x16x32_bf16 v[24:27], v[136:139], v[230:233], v[24:27]
	v_mfma_f32_16x16x32_bf16 v[12:15], v[128:131], v[238:241], v[12:15]
	v_mfma_f32_16x16x32_bf16 v[8:11], v[136:139], v[238:241], v[8:11]
	v_mfma_f32_16x16x32_bf16 v[60:63], v[132:135], v[164:167], v[60:63]
	v_mfma_f32_16x16x32_bf16 v[56:59], v[140:143], v[164:167], v[56:59]
	v_mfma_f32_16x16x32_bf16 v[44:47], v[132:135], v[226:229], v[44:47]
	v_mfma_f32_16x16x32_bf16 v[40:43], v[140:143], v[226:229], v[40:43]
	v_mfma_f32_16x16x32_bf16 v[28:31], v[132:135], v[234:237], v[28:31]
	v_mfma_f32_16x16x32_bf16 v[24:27], v[140:143], v[234:237], v[24:27]
	v_mfma_f32_16x16x32_bf16 v[12:15], v[132:135], v[242:245], v[12:15]
	v_mfma_f32_16x16x32_bf16 v[8:11], v[140:143], v[242:245], v[8:11]
	v_mfma_f32_16x16x32_bf16 v[52:55], v[144:147], v[160:163], v[52:55]
	v_mfma_f32_16x16x32_bf16 v[48:51], v[152:155], v[160:163], v[48:51]
	v_mfma_f32_16x16x32_bf16 v[36:39], v[144:147], v[188:191], v[36:39]
	v_mfma_f32_16x16x32_bf16 v[32:35], v[152:155], v[188:191], v[32:35]
	v_mfma_f32_16x16x32_bf16 v[20:23], v[144:147], v[230:233], v[20:23]
	v_mfma_f32_16x16x32_bf16 v[16:19], v[152:155], v[230:233], v[16:19]
	v_mfma_f32_16x16x32_bf16 v[4:7], v[144:147], v[238:241], v[4:7]
	v_mfma_f32_16x16x32_bf16 v[0:3], v[152:155], v[238:241], v[0:3]
	v_mfma_f32_16x16x32_bf16 v[52:55], v[148:151], v[164:167], v[52:55]
	v_mfma_f32_16x16x32_bf16 v[48:51], v[156:159], v[164:167], v[48:51]
	v_mfma_f32_16x16x32_bf16 v[36:39], v[148:151], v[226:229], v[36:39]
	v_mfma_f32_16x16x32_bf16 v[32:35], v[156:159], v[226:229], v[32:35]
	v_mfma_f32_16x16x32_bf16 v[20:23], v[148:151], v[234:237], v[20:23]
	v_mfma_f32_16x16x32_bf16 v[16:19], v[156:159], v[234:237], v[16:19]
	v_mfma_f32_16x16x32_bf16 v[4:7], v[148:151], v[242:245], v[4:7]
	v_mfma_f32_16x16x32_bf16 v[0:3], v[156:159], v[242:245], v[0:3]
	s_setprio 0
	s_barrier
	s_add_i32 s56, 0, 0x18000
	s_add_i32 s57, 0, 0x1c000
	v_add_u32_e32 v140, s56, v196
	v_add_u32_e32 v156, s57, v196
	ds_read_b128 v[128:131], v140
	ds_read_b128 v[132:135], v140 offset:1024
	ds_read_b128 v[136:139], v140 offset:2048
	ds_read_b128 v[140:143], v140 offset:3072
	ds_read_b128 v[144:147], v156
	ds_read_b128 v[148:151], v156 offset:1024
	ds_read_b128 v[152:155], v156 offset:2048
	ds_read_b128 v[156:159], v156 offset:3072
	s_add_u32 s0, s36, 0xb0000
	s_addc_u32 s1, s37, 0
	s_mov_b32 m0, s41
	v_lshl_add_u64 v[252:253], s[0:1], 0, v[172:173]
	ds_read_b128 v[160:163], v220 offset:32768
	ds_read_b128 v[164:167], v220 offset:33792
	ds_read_b128 v[188:191], v220 offset:34816
	ds_read_b128 v[226:229], v220 offset:35840
	ds_read_b128 v[230:233], v220 offset:36864
	ds_read_b128 v[234:237], v220 offset:37888
	ds_read_b128 v[238:241], v220 offset:38912
	ds_read_b128 v[242:245], v220 offset:39936
	global_load_lds_dwordx4 v[252:253], off
	v_lshl_add_u64 v[252:253], s[0:1], 0, v[176:177]
	s_mov_b32 m0, s42
	s_nop 0
	global_load_lds_dwordx4 v[252:253], off
	s_waitcnt vmcnt(8)
	s_waitcnt lgkmcnt(0)
	s_barrier
	s_setprio 1
	s_waitcnt lgkmcnt(0)
	v_mfma_f32_16x16x32_bf16 v[124:127], v[128:131], v[160:163], v[124:127]
	v_mfma_f32_16x16x32_bf16 v[120:123], v[136:139], v[160:163], v[120:123]
	v_mfma_f32_16x16x32_bf16 v[108:111], v[128:131], v[188:191], v[108:111]
	v_mfma_f32_16x16x32_bf16 v[104:107], v[136:139], v[188:191], v[104:107]
	v_mfma_f32_16x16x32_bf16 v[92:95], v[128:131], v[230:233], v[92:95]
	v_mfma_f32_16x16x32_bf16 v[88:91], v[136:139], v[230:233], v[88:91]
	v_mfma_f32_16x16x32_bf16 v[76:79], v[128:131], v[238:241], v[76:79]
	v_mfma_f32_16x16x32_bf16 v[72:75], v[136:139], v[238:241], v[72:75]
	v_mfma_f32_16x16x32_bf16 v[124:127], v[132:135], v[164:167], v[124:127]
	v_mfma_f32_16x16x32_bf16 v[120:123], v[140:143], v[164:167], v[120:123]
	v_mfma_f32_16x16x32_bf16 v[108:111], v[132:135], v[226:229], v[108:111]
	v_mfma_f32_16x16x32_bf16 v[104:107], v[140:143], v[226:229], v[104:107]
	v_mfma_f32_16x16x32_bf16 v[92:95], v[132:135], v[234:237], v[92:95]
	v_mfma_f32_16x16x32_bf16 v[88:91], v[140:143], v[234:237], v[88:91]
	v_mfma_f32_16x16x32_bf16 v[76:79], v[132:135], v[242:245], v[76:79]
	v_mfma_f32_16x16x32_bf16 v[72:75], v[140:143], v[242:245], v[72:75]
	v_mfma_f32_16x16x32_bf16 v[116:119], v[144:147], v[160:163], v[116:119]
	v_mfma_f32_16x16x32_bf16 v[112:115], v[152:155], v[160:163], v[112:115]
	v_mfma_f32_16x16x32_bf16 v[100:103], v[144:147], v[188:191], v[100:103]
	v_mfma_f32_16x16x32_bf16 v[96:99], v[152:155], v[188:191], v[96:99]
	v_mfma_f32_16x16x32_bf16 v[84:87], v[144:147], v[230:233], v[84:87]
	v_mfma_f32_16x16x32_bf16 v[80:83], v[152:155], v[230:233], v[80:83]
	v_mfma_f32_16x16x32_bf16 v[68:71], v[144:147], v[238:241], v[68:71]
	v_mfma_f32_16x16x32_bf16 v[64:67], v[152:155], v[238:241], v[64:67]
	v_mfma_f32_16x16x32_bf16 v[116:119], v[148:151], v[164:167], v[116:119]
	v_mfma_f32_16x16x32_bf16 v[112:115], v[156:159], v[164:167], v[112:115]
	v_mfma_f32_16x16x32_bf16 v[100:103], v[148:151], v[226:229], v[100:103]
	v_mfma_f32_16x16x32_bf16 v[96:99], v[156:159], v[226:229], v[96:99]
	v_mfma_f32_16x16x32_bf16 v[84:87], v[148:151], v[234:237], v[84:87]
	v_mfma_f32_16x16x32_bf16 v[80:83], v[156:159], v[234:237], v[80:83]
	v_mfma_f32_16x16x32_bf16 v[68:71], v[148:151], v[242:245], v[68:71]
	v_mfma_f32_16x16x32_bf16 v[64:67], v[156:159], v[242:245], v[64:67]
	s_setprio 0
	s_barrier
; #define PG8_STAGE(bufoff, gbase, voff) do { _Pragma("unroll") for (int _i = 0; _i < 2; ++_i) \
;         __builtin_amdgcn_global_load_lds((const unsigned*)((const char*)(gbase) + (voff)[_i]), (PG8_LAS unsigned*)(lds + (bufoff) + ldsw + _i * 8192), 16, 0, 0); } while (0)
; #define PG8_LDA(dst, b, h) do { _Pragma("unroll") for (int m = 0; m < 4; ++m) _Pragma("unroll") for (int k = 0; k < 2; ++k) dst[m][k] = *(const PG8_LAS bf16x8*)(lds + PG8_SA(b, h) + aoff + m * 2048 + k * 1024); } while (0)
; #define PG8_MMA(ai, bj, At, Bt) do { __builtin_amdgcn_s_setprio(1); _Pragma("unroll") for (int m = 0; m < 4; ++m) _Pragma("unroll") for (int n = 0; n < 2; ++n) _Pragma("unroll") for (int k = 0; k < 2; ++k) \
;         acc[ai][bj][m][n] = __builtin_amdgcn_mfma_f32_16x16x32_bf16(Bt[n][k], At[m][k], acc[ai][bj][m][n], 0, 0, 0); __builtin_amdgcn_s_setprio(0); } while (0)
; #define PG8_WAIT_V(n) asm volatile("s_waitcnt vmcnt(" #n ")" ::: "memory")
; #define PG8_WAIT_L(n) asm volatile("s_waitcnt lgkmcnt(" #n ")" ::: "memory")
; #define PG8_BAR __builtin_amdgcn_s_barrier()
; #define PG8_SCHED __builtin_amdgcn_sched_barrier(0)
; template <class Epi, class Sched, bool ALIGN_EPI = false, bool SP2 = false>
; __device__ __forceinline__ void gemm_phase(PG8_LAS unsigned char* lds, const Gemm g, const Sched& S, const Epi& E) {
;     ...
;             PG8_LDA(At, 1, 1); PG8_STAGE(PG8_SB(1, 0), b3, voffB); PG8_STAGE(PG8_SB(1, 1), b3 + hstep, voffB); PG8_STAGE(PG8_SA(1, 0), a3, voffA);
;             PG8_WAIT_V(8); PG8_WAIT_L(0); PG8_BAR; PG8_MMA(1, 0, At, B0); PG8_MMA(1, 1, At, B1); PG8_BAR; PG8_SCHED;
	s_add_i32 s0, s56, s38
	v_lshl_add_u64 v[192:193], v[192:193], 0, s[22:23]
	s_mov_b32 m0, s0
	ds_read_b128 v[160:163], v220 offset:49152
	ds_read_b128 v[164:167], v220 offset:50176
	ds_read_b128 v[188:191], v220 offset:51200
	ds_read_b128 v[226:229], v220 offset:52224
	ds_read_b128 v[230:233], v220 offset:53248
	ds_read_b128 v[234:237], v220 offset:54272
	ds_read_b128 v[238:241], v220 offset:55296
	ds_read_b128 v[242:245], v220 offset:56320
	global_load_lds_dwordx4 v[192:193], off
	s_add_i32 m0, s0, 0x2000
	s_add_u32 s0, s34, 0xb0080
	v_lshl_add_u64 v[192:193], v[246:247], 0, s[22:23]
	s_addc_u32 s1, s35, 0
	s_add_i32 s34, s57, s38
	global_load_lds_dwordx4 v[192:193], off
	v_lshl_add_u64 v[192:193], s[0:1], 0, v[174:175]
	s_mov_b32 m0, s34
	s_nop 0
	global_load_lds_dwordx4 v[192:193], off
	v_lshl_add_u64 v[192:193], s[0:1], 0, v[178:179]
	s_add_i32 m0, s34, 0x2000
	s_nop 0
	global_load_lds_dwordx4 v[192:193], off
	v_lshl_add_u64 v[192:193], v[248:249], 0, s[22:23]
	s_mov_b32 m0, s44
	s_nop 0
	global_load_lds_dwordx4 v[192:193], off
	v_lshl_add_u64 v[192:193], v[250:251], 0, s[22:23]
	s_mov_b32 m0, s45
	s_nop 0
	global_load_lds_dwordx4 v[192:193], off
	s_waitcnt vmcnt(8)
	s_waitcnt lgkmcnt(0)
	s_barrier
	s_setprio 1
	s_waitcnt lgkmcnt(0)
	v_mfma_f32_16x16x32_bf16 v[60:63], v[128:131], v[160:163], v[60:63]
	v_mfma_f32_16x16x32_bf16 v[56:59], v[136:139], v[160:163], v[56:59]
	v_mfma_f32_16x16x32_bf16 v[44:47], v[128:131], v[188:191], v[44:47]
	v_mfma_f32_16x16x32_bf16 v[40:43], v[136:139], v[188:191], v[40:43]
	v_mfma_f32_16x16x32_bf16 v[28:31], v[128:131], v[230:233], v[28:31]
	v_mfma_f32_16x16x32_bf16 v[24:27], v[136:139], v[230:233], v[24:27]
	v_mfma_f32_16x16x32_bf16 v[12:15], v[128:131], v[238:241], v[12:15]
	v_mfma_f32_16x16x32_bf16 v[8:11], v[136:139], v[238:241], v[8:11]
	v_mfma_f32_16x16x32_bf16 v[60:63], v[132:135], v[164:167], v[60:63]
	v_mfma_f32_16x16x32_bf16 v[56:59], v[140:143], v[164:167], v[56:59]
	v_mfma_f32_16x16x32_bf16 v[44:47], v[132:135], v[226:229], v[44:47]
	v_mfma_f32_16x16x32_bf16 v[40:43], v[140:143], v[226:229], v[40:43]
	v_mfma_f32_16x16x32_bf16 v[28:31], v[132:135], v[234:237], v[28:31]
	v_mfma_f32_16x16x32_bf16 v[24:27], v[140:143], v[234:237], v[24:27]
	v_mfma_f32_16x16x32_bf16 v[12:15], v[132:135], v[242:245], v[12:15]
	v_mfma_f32_16x16x32_bf16 v[8:11], v[140:143], v[242:245], v[8:11]
	v_mfma_f32_16x16x32_bf16 v[52:55], v[144:147], v[160:163], v[52:55]
	v_mfma_f32_16x16x32_bf16 v[48:51], v[152:155], v[160:163], v[48:51]
	v_mfma_f32_16x16x32_bf16 v[36:39], v[144:147], v[188:191], v[36:39]
	v_mfma_f32_16x16x32_bf16 v[32:35], v[152:155], v[188:191], v[32:35]
	v_mfma_f32_16x16x32_bf16 v[20:23], v[144:147], v[230:233], v[20:23]
	v_mfma_f32_16x16x32_bf16 v[16:19], v[152:155], v[230:233], v[16:19]
	v_mfma_f32_16x16x32_bf16 v[4:7], v[144:147], v[238:241], v[4:7]
	v_mfma_f32_16x16x32_bf16 v[0:3], v[152:155], v[238:241], v[0:3]
	v_mfma_f32_16x16x32_bf16 v[52:55], v[148:151], v[164:167], v[52:55]
	v_mfma_f32_16x16x32_bf16 v[48:51], v[156:159], v[164:167], v[48:51]
	v_mfma_f32_16x16x32_bf16 v[36:39], v[148:151], v[226:229], v[36:39]
	v_mfma_f32_16x16x32_bf16 v[32:35], v[156:159], v[226:229], v[32:35]
	v_mfma_f32_16x16x32_bf16 v[20:23], v[148:151], v[234:237], v[20:23]
	v_mfma_f32_16x16x32_bf16 v[16:19], v[156:159], v[234:237], v[16:19]
	v_mfma_f32_16x16x32_bf16 v[4:7], v[148:151], v[242:245], v[4:7]
	v_mfma_f32_16x16x32_bf16 v[0:3], v[156:159], v[242:245], v[0:3]
	s_setprio 0
	s_barrier
	s_add_i32 s55, s55, 2
	s_add_u32 s33, s33, 0x100
	s_addc_u32 s54, s54, 0
	s_cmp_gt_u32 s55, 41
	s_mov_b64 s[0:1], s[30:31]
	s_cbranch_scc0 .LBB0_232
	s_and_b64 vcc, exec, s[24:25]
	s_cbranch_vccz .LBB0_235
	s_barrier

; #define PG8_STAGE(bufoff, gbase, voff) do { _Pragma("unroll") for (int _i = 0; _i < 2; ++_i) \
;         __builtin_amdgcn_global_load_lds((const unsigned*)((const char*)(gbase) + (voff)[_i]), (PG8_LAS unsigned*)(lds + (bufoff) + ldsw + _i * 8192), 16, 0, 0); } while (0)
; #define PG8_LDA(dst, b, h) do { _Pragma("unroll") for (int m = 0; m < 4; ++m) _Pragma("unroll") for (int k = 0; k < 2; ++k) dst[m][k] = *(const PG8_LAS bf16x8*)(lds + PG8_SA(b, h) + aoff + m * 2048 + k * 1024); } while (0)
; #define PG8_LDB(dst, b, h) do { _Pragma("unroll") for (int n = 0; n < 2; ++n) _Pragma("unroll") for (int k = 0; k < 2; ++k) dst[n][k] = *(const PG8_LAS bf16x8*)(lds + PG8_SB(b, h) + boff + n * 2048 + k * 1024); } while (0)
; #define PG8_MMA(ai, bj, At, Bt) do { __builtin_amdgcn_s_setprio(1); _Pragma("unroll") for (int m = 0; m < 4; ++m) _Pragma("unroll") for (int n = 0; n < 2; ++n) _Pragma("unroll") for (int k = 0; k < 2; ++k) \
;         acc[ai][bj][m][n] = __builtin_amdgcn_mfma_f32_16x16x32_bf16(Bt[n][k], At[m][k], acc[ai][bj][m][n], 0, 0, 0); __builtin_amdgcn_s_setprio(0); } while (0)
; #define PG8_WAIT_V(n) asm volatile("s_waitcnt vmcnt(" #n ")" ::: "memory")
; #define PG8_WAIT_L(n) asm volatile("s_waitcnt lgkmcnt(" #n ")" ::: "memory")
; #define PG8_BAR __builtin_amdgcn_s_barrier()
; #define PG8_SCHED __builtin_amdgcn_sched_barrier(0)
; template <class Epi, class Sched, bool ALIGN_EPI = false, bool SP2 = false>
; __device__ __forceinline__ void gemm_phase(PG8_LAS unsigned char* lds, const Gemm g, const Sched& S, const Epi& E) {
;     ...
;             const bool last = (t == nt - 2);
;             const char* a1 = cA + (size_t)(t + 1) * kstep;
;             const char* a2 = last ? nA : cA + (size_t)(t + 2) * kstep; const char* b2 = last ? nB : cB + (size_t)(t + 2) * kstep;
;             const char* a3 = a2 + kstep; const char* b3 = b2 + kstep;
;             if (last && has_next) S.a_ready(nxt);
;             if constexpr (SP2) {
;             PG8_LDB(B0, 0, 0); PG8_LDB(B1, 0, 1); PG8_SCHED; PG8_LDA(At, 0, 0); PG8_STAGE(PG8_SA(1, 1), a1 + hstep, voffA);
;             PG8_WAIT_V(8); PG8_WAIT_L(0); PG8_BAR; PG8_MMA(0, 0, At, B0); PG8_MMA(0, 1, At, B1); PG8_BAR; PG8_SCHED;
;             PG8_LDA(At, 0, 1); PG8_STAGE(PG8_SB(0, 0), b2, voffB); PG8_STAGE(PG8_SB(0, 1), b2 + hstep, voffB); PG8_STAGE(PG8_SA(0, 0), a2, voffA);
.LBB0_369:
	ds_read_b128 v[128:131], v169
	ds_read_b128 v[150:153], v169 offset:1024
	ds_read_b128 v[154:157], v169 offset:2048
	ds_read_b128 v[158:161], v169 offset:3072
	ds_read_b128 v[176:179], v172
	ds_read_b128 v[180:183], v172 offset:1024
	ds_read_b128 v[184:187], v172 offset:2048
	ds_read_b128 v[188:191], v172 offset:3072
	s_add_u32 s36, s0, 0xfffc0080
	s_addc_u32 s37, s1, -1
	s_cmp_eq_u32 s53, 12
	s_cselect_b32 s39, s7, s37
	s_cselect_b32 s38, s27, s36
	s_cselect_b32 s37, s25, s52
	s_cselect_b32 s36, s33, s51
	v_lshl_add_u64 v[162:163], s[0:1], 0, v[142:143]
	s_add_i32 m0, s35, 0xc000
	ds_read_b128 v[202:205], v173
	ds_read_b128 v[206:209], v173 offset:1024
	ds_read_b128 v[210:213], v173 offset:2048
	ds_read_b128 v[214:217], v173 offset:3072
	ds_read_b128 v[218:221], v173 offset:4096
	ds_read_b128 v[222:225], v173 offset:5120
	ds_read_b128 v[226:229], v173 offset:6144
	ds_read_b128 v[230:233], v173 offset:7168
	global_load_lds_dwordx4 v[162:163], off
	v_lshl_add_u64 v[162:163], s[0:1], 0, v[144:145]
	s_add_i32 m0, s35, 0xe000
	s_nop 0
	global_load_lds_dwordx4 v[162:163], off
	s_waitcnt vmcnt(8)
	s_waitcnt lgkmcnt(0)
	s_barrier
	s_setprio 1
	s_waitcnt lgkmcnt(0)
	v_mfma_f32_16x16x32_bf16 v[124:127], v[128:131], v[202:205], v[124:127]
	v_mfma_f32_16x16x32_bf16 v[120:123], v[154:157], v[202:205], v[120:123]
	v_mfma_f32_16x16x32_bf16 v[108:111], v[128:131], v[210:213], v[108:111]
	v_mfma_f32_16x16x32_bf16 v[104:107], v[154:157], v[210:213], v[104:107]
	v_mfma_f32_16x16x32_bf16 v[92:95], v[128:131], v[218:221], v[92:95]
	v_mfma_f32_16x16x32_bf16 v[88:91], v[154:157], v[218:221], v[88:91]
	v_mfma_f32_16x16x32_bf16 v[76:79], v[128:131], v[226:229], v[76:79]
	v_mfma_f32_16x16x32_bf16 v[72:75], v[154:157], v[226:229], v[72:75]
	v_mfma_f32_16x16x32_bf16 v[124:127], v[150:153], v[206:209], v[124:127]
	v_mfma_f32_16x16x32_bf16 v[120:123], v[158:161], v[206:209], v[120:123]
	v_mfma_f32_16x16x32_bf16 v[108:111], v[150:153], v[214:217], v[108:111]
	v_mfma_f32_16x16x32_bf16 v[104:107], v[158:161], v[214:217], v[104:107]
	v_mfma_f32_16x16x32_bf16 v[92:95], v[150:153], v[222:225], v[92:95]
	v_mfma_f32_16x16x32_bf16 v[88:91], v[158:161], v[222:225], v[88:91]
	v_mfma_f32_16x16x32_bf16 v[76:79], v[150:153], v[230:233], v[76:79]
	v_mfma_f32_16x16x32_bf16 v[72:75], v[158:161], v[230:233], v[72:75]
	v_mfma_f32_16x16x32_bf16 v[116:119], v[176:179], v[202:205], v[116:119]
	v_mfma_f32_16x16x32_bf16 v[112:115], v[184:187], v[202:205], v[112:115]
	v_mfma_f32_16x16x32_bf16 v[100:103], v[176:179], v[210:213], v[100:103]
	v_mfma_f32_16x16x32_bf16 v[96:99], v[184:187], v[210:213], v[96:99]
	v_mfma_f32_16x16x32_bf16 v[84:87], v[176:179], v[218:221], v[84:87]
	v_mfma_f32_16x16x32_bf16 v[80:83], v[184:187], v[218:221], v[80:83]
	v_mfma_f32_16x16x32_bf16 v[68:71], v[176:179], v[226:229], v[68:71]
	v_mfma_f32_16x16x32_bf16 v[64:67], v[184:187], v[226:229], v[64:67]
	v_mfma_f32_16x16x32_bf16 v[116:119], v[180:183], v[206:209], v[116:119]
	v_mfma_f32_16x16x32_bf16 v[112:115], v[188:191], v[206:209], v[112:115]
	v_mfma_f32_16x16x32_bf16 v[100:103], v[180:183], v[214:217], v[100:103]
	v_mfma_f32_16x16x32_bf16 v[96:99], v[188:191], v[214:217], v[96:99]
	v_mfma_f32_16x16x32_bf16 v[84:87], v[180:183], v[222:225], v[84:87]
	v_mfma_f32_16x16x32_bf16 v[80:83], v[188:191], v[222:225], v[80:83]
	v_mfma_f32_16x16x32_bf16 v[68:71], v[180:183], v[230:233], v[68:71]
	v_mfma_f32_16x16x32_bf16 v[64:67], v[188:191], v[230:233], v[64:67]
	s_setprio 0
	s_barrier
	s_add_i32 s54, s49, s40
	v_lshl_add_u64 v[162:163], s[36:37], 0, v[134:135]
	s_mov_b32 m0, s54
	ds_read_b128 v[202:205], v173 offset:16384
	ds_read_b128 v[206:209], v173 offset:17408
	ds_read_b128 v[210:213], v173 offset:18432
	ds_read_b128 v[214:217], v173 offset:19456
	ds_read_b128 v[218:221], v173 offset:20480
	ds_read_b128 v[222:225], v173 offset:21504
	ds_read_b128 v[226:229], v173 offset:22528
	ds_read_b128 v[230:233], v173 offset:23552
	global_load_lds_dwordx4 v[162:163], off
	s_add_i32 m0, s54, 0x2000
	s_add_u32 s54, s36, 0x40000
	v_lshl_add_u64 v[192:193], s[36:37], 0, v[138:139]
	s_addc_u32 s55, s37, 0
	s_add_i32 s56, s50, s40
	global_load_lds_dwordx4 v[192:193], off
	v_lshl_add_u64 v[196:197], s[54:55], 0, v[134:135]
	s_mov_b32 m0, s56
	v_lshl_add_u64 v[234:235], s[38:39], 0, v[136:137]
	global_load_lds_dwordx4 v[196:197], off
	v_lshl_add_u64 v[196:197], s[54:55], 0, v[138:139]
	s_add_i32 m0, s56, 0x2000
	s_nop 0
	global_load_lds_dwordx4 v[196:197], off
	v_lshl_add_u64 v[196:197], s[38:39], 0, v[132:133]
	s_mov_b32 m0, s35
	s_nop 0
	global_load_lds_dwordx4 v[196:197], off
	s_mov_b32 m0, s41
	s_nop 0
	global_load_lds_dwordx4 v[234:235], off
	s_waitcnt vmcnt(8)
	s_waitcnt lgkmcnt(0)
	s_barrier
; #define PG8_STAGE(bufoff, gbase, voff) do { _Pragma("unroll") for (int _i = 0; _i < 2; ++_i) \
;         __builtin_amdgcn_global_load_lds((const unsigned*)((const char*)(gbase) + (voff)[_i]), (PG8_LAS unsigned*)(lds + (bufoff) + ldsw + _i * 8192), 16, 0, 0); } while (0)
; #define PG8_LDA(dst, b, h) do { _Pragma("unroll") for (int m = 0; m < 4; ++m) _Pragma("unroll") for (int k = 0; k < 2; ++k) dst[m][k] = *(const PG8_LAS bf16x8*)(lds + PG8_SA(b, h) + aoff + m * 2048 + k * 1024); } while (0)
; #define PG8_LDB(dst, b, h) do { _Pragma("unroll") for (int n = 0; n < 2; ++n) _Pragma("unroll") for (int k = 0; k < 2; ++k) dst[n][k] = *(const PG8_LAS bf16x8*)(lds + PG8_SB(b, h) + boff + n * 2048 + k * 1024); } while (0)
; #define PG8_MMA(ai, bj, At, Bt) do { __builtin_amdgcn_s_setprio(1); _Pragma("unroll") for (int m = 0; m < 4; ++m) _Pragma("unroll") for (int n = 0; n < 2; ++n) _Pragma("unroll") for (int k = 0; k < 2; ++k) \
;         acc[ai][bj][m][n] = __builtin_amdgcn_mfma_f32_16x16x32_bf16(Bt[n][k], At[m][k], acc[ai][bj][m][n], 0, 0, 0); __builtin_amdgcn_s_setprio(0); } while (0)
; #define PG8_WAIT_V(n) asm volatile("s_waitcnt vmcnt(" #n ")" ::: "memory")
; #define PG8_WAIT_L(n) asm volatile("s_waitcnt lgkmcnt(" #n ")" ::: "memory")
; #define PG8_BAR __builtin_amdgcn_s_barrier()
; #define PG8_SCHED __builtin_amdgcn_sched_barrier(0)
; template <class Epi, class Sched, bool ALIGN_EPI = false, bool SP2 = false>
; __device__ __forceinline__ void gemm_phase(PG8_LAS unsigned char* lds, const Gemm g, const Sched& S, const Epi& E) {
;     ...
;             PG8_WAIT_V(8); PG8_WAIT_L(0); PG8_BAR; PG8_MMA(1, 0, At, B0); PG8_MMA(1, 1, At, B1); PG8_BAR; PG8_SCHED;
;             PG8_LDB(B0, 1, 0); PG8_LDB(B1, 1, 1); PG8_SCHED; PG8_LDA(At, 1, 0); PG8_STAGE(PG8_SA(0, 1), a2 + hstep, voffA);
;             PG8_WAIT_V(8); PG8_WAIT_L(0); PG8_BAR; PG8_MMA(0, 0, At, B0); PG8_MMA(0, 1, At, B1); PG8_BAR; PG8_SCHED;
	s_setprio 1
	s_waitcnt lgkmcnt(0)
	v_mfma_f32_16x16x32_bf16 v[60:63], v[128:131], v[202:205], v[60:63]
	v_mfma_f32_16x16x32_bf16 v[56:59], v[154:157], v[202:205], v[56:59]
	v_mfma_f32_16x16x32_bf16 v[44:47], v[128:131], v[210:213], v[44:47]
	v_mfma_f32_16x16x32_bf16 v[40:43], v[154:157], v[210:213], v[40:43]
	v_mfma_f32_16x16x32_bf16 v[28:31], v[128:131], v[218:221], v[28:31]
	v_mfma_f32_16x16x32_bf16 v[24:27], v[154:157], v[218:221], v[24:27]
	v_mfma_f32_16x16x32_bf16 v[12:15], v[128:131], v[226:229], v[12:15]
	v_mfma_f32_16x16x32_bf16 v[8:11], v[154:157], v[226:229], v[8:11]
	v_mfma_f32_16x16x32_bf16 v[60:63], v[150:153], v[206:209], v[60:63]
	v_mfma_f32_16x16x32_bf16 v[56:59], v[158:161], v[206:209], v[56:59]
	v_mfma_f32_16x16x32_bf16 v[44:47], v[150:153], v[214:217], v[44:47]
	v_mfma_f32_16x16x32_bf16 v[40:43], v[158:161], v[214:217], v[40:43]
	v_mfma_f32_16x16x32_bf16 v[28:31], v[150:153], v[222:225], v[28:31]
	v_mfma_f32_16x16x32_bf16 v[24:27], v[158:161], v[222:225], v[24:27]
	v_mfma_f32_16x16x32_bf16 v[12:15], v[150:153], v[230:233], v[12:15]
	v_mfma_f32_16x16x32_bf16 v[8:11], v[158:161], v[230:233], v[8:11]
	v_mfma_f32_16x16x32_bf16 v[52:55], v[176:179], v[202:205], v[52:55]
	v_mfma_f32_16x16x32_bf16 v[48:51], v[184:187], v[202:205], v[48:51]
	v_mfma_f32_16x16x32_bf16 v[36:39], v[176:179], v[210:213], v[36:39]
	v_mfma_f32_16x16x32_bf16 v[32:35], v[184:187], v[210:213], v[32:35]
	v_mfma_f32_16x16x32_bf16 v[20:23], v[176:179], v[218:221], v[20:23]
	v_mfma_f32_16x16x32_bf16 v[16:19], v[184:187], v[218:221], v[16:19]
	v_mfma_f32_16x16x32_bf16 v[4:7], v[176:179], v[226:229], v[4:7]
	v_mfma_f32_16x16x32_bf16 v[0:3], v[184:187], v[226:229], v[0:3]
	v_mfma_f32_16x16x32_bf16 v[52:55], v[180:183], v[206:209], v[52:55]
	v_mfma_f32_16x16x32_bf16 v[48:51], v[188:191], v[206:209], v[48:51]
	v_mfma_f32_16x16x32_bf16 v[36:39], v[180:183], v[214:217], v[36:39]
	v_mfma_f32_16x16x32_bf16 v[32:35], v[188:191], v[214:217], v[32:35]
	v_mfma_f32_16x16x32_bf16 v[20:23], v[180:183], v[222:225], v[20:23]
	v_mfma_f32_16x16x32_bf16 v[16:19], v[188:191], v[222:225], v[16:19]
	v_mfma_f32_16x16x32_bf16 v[4:7], v[180:183], v[230:233], v[4:7]
	v_mfma_f32_16x16x32_bf16 v[0:3], v[188:191], v[230:233], v[0:3]
	s_setprio 0
	s_barrier
	s_add_i32 s54, 0, 0x18000
	v_add_u32_e32 v140, s54, v165
	s_add_i32 s55, 0, 0x1c000
	ds_read_b128 v[128:131], v140
	ds_read_b128 v[150:153], v140 offset:1024
	ds_read_b128 v[154:157], v140 offset:2048
	ds_read_b128 v[158:161], v140 offset:3072
	v_add_u32_e32 v140, s55, v165
	ds_read_b128 v[176:179], v140
	ds_read_b128 v[180:183], v140 offset:1024
	ds_read_b128 v[184:187], v140 offset:2048
	ds_read_b128 v[188:191], v140 offset:3072
	s_add_u32 s38, s38, 0x40000
	s_addc_u32 s39, s39, 0
	s_mov_b32 m0, s42
	v_lshl_add_u64 v[236:237], s[38:39], 0, v[132:133]
	ds_read_b128 v[202:205], v173 offset:32768
	ds_read_b128 v[206:209], v173 offset:33792
	ds_read_b128 v[210:213], v173 offset:34816
	ds_read_b128 v[214:217], v173 offset:35840
	ds_read_b128 v[218:221], v173 offset:36864
	ds_read_b128 v[222:225], v173 offset:37888
	ds_read_b128 v[226:229], v173 offset:38912
	ds_read_b128 v[230:233], v173 offset:39936
	global_load_lds_dwordx4 v[236:237], off
	v_lshl_add_u64 v[236:237], s[38:39], 0, v[136:137]
	s_mov_b32 m0, s43
	s_nop 0
	global_load_lds_dwordx4 v[236:237], off
	s_waitcnt vmcnt(8)
	s_waitcnt lgkmcnt(0)
	s_barrier
	s_setprio 1
	s_waitcnt lgkmcnt(0)
	v_mfma_f32_16x16x32_bf16 v[124:127], v[128:131], v[202:205], v[124:127]
	v_mfma_f32_16x16x32_bf16 v[120:123], v[154:157], v[202:205], v[120:123]
	v_mfma_f32_16x16x32_bf16 v[108:111], v[128:131], v[210:213], v[108:111]
	v_mfma_f32_16x16x32_bf16 v[104:107], v[154:157], v[210:213], v[104:107]
	v_mfma_f32_16x16x32_bf16 v[92:95], v[128:131], v[218:221], v[92:95]
	v_mfma_f32_16x16x32_bf16 v[88:91], v[154:157], v[218:221], v[88:91]
	v_mfma_f32_16x16x32_bf16 v[76:79], v[128:131], v[226:229], v[76:79]
	v_mfma_f32_16x16x32_bf16 v[72:75], v[154:157], v[226:229], v[72:75]
	v_mfma_f32_16x16x32_bf16 v[124:127], v[150:153], v[206:209], v[124:127]
	v_mfma_f32_16x16x32_bf16 v[120:123], v[158:161], v[206:209], v[120:123]
	v_mfma_f32_16x16x32_bf16 v[108:111], v[150:153], v[214:217], v[108:111]
	v_mfma_f32_16x16x32_bf16 v[104:107], v[158:161], v[214:217], v[104:107]
	v_mfma_f32_16x16x32_bf16 v[92:95], v[150:153], v[222:225], v[92:95]
	v_mfma_f32_16x16x32_bf16 v[88:91], v[158:161], v[222:225], v[88:91]
	v_mfma_f32_16x16x32_bf16 v[76:79], v[150:153], v[230:233], v[76:79]
	v_mfma_f32_16x16x32_bf16 v[72:75], v[158:161], v[230:233], v[72:75]
	v_mfma_f32_16x16x32_bf16 v[116:119], v[176:179], v[202:205], v[116:119]
	v_mfma_f32_16x16x32_bf16 v[112:115], v[184:187], v[202:205], v[112:115]
	v_mfma_f32_16x16x32_bf16 v[100:103], v[176:179], v[210:213], v[100:103]
	v_mfma_f32_16x16x32_bf16 v[96:99], v[184:187], v[210:213], v[96:99]
	v_mfma_f32_16x16x32_bf16 v[84:87], v[176:179], v[218:221], v[84:87]
	v_mfma_f32_16x16x32_bf16 v[80:83], v[184:187], v[218:221], v[80:83]
	v_mfma_f32_16x16x32_bf16 v[68:71], v[176:179], v[226:229], v[68:71]
	v_mfma_f32_16x16x32_bf16 v[64:67], v[184:187], v[226:229], v[64:67]
	v_mfma_f32_16x16x32_bf16 v[116:119], v[180:183], v[206:209], v[116:119]
	v_mfma_f32_16x16x32_bf16 v[112:115], v[188:191], v[206:209], v[112:115]
	v_mfma_f32_16x16x32_bf16 v[100:103], v[180:183], v[214:217], v[100:103]
	v_mfma_f32_16x16x32_bf16 v[96:99], v[188:191], v[214:217], v[96:99]
	v_mfma_f32_16x16x32_bf16 v[84:87], v[180:183], v[222:225], v[84:87]
	v_mfma_f32_16x16x32_bf16 v[80:83], v[188:191], v[222:225], v[80:83]
	v_mfma_f32_16x16x32_bf16 v[68:71], v[180:183], v[230:233], v[68:71]
	v_mfma_f32_16x16x32_bf16 v[64:67], v[188:191], v[230:233], v[64:67]
	s_setprio 0
	s_barrier
; #define PG8_STAGE(bufoff, gbase, voff) do { _Pragma("unroll") for (int _i = 0; _i < 2; ++_i) \
;         __builtin_amdgcn_global_load_lds((const unsigned*)((const char*)(gbase) + (voff)[_i]), (PG8_LAS unsigned*)(lds + (bufoff) + ldsw + _i * 8192), 16, 0, 0); } while (0)
; #define PG8_LDA(dst, b, h) do { _Pragma("unroll") for (int m = 0; m < 4; ++m) _Pragma("unroll") for (int k = 0; k < 2; ++k) dst[m][k] = *(const PG8_LAS bf16x8*)(lds + PG8_SA(b, h) + aoff + m * 2048 + k * 1024); } while (0)
; #define PG8_MMA(ai, bj, At, Bt) do { __builtin_amdgcn_s_setprio(1); _Pragma("unroll") for (int m = 0; m < 4; ++m) _Pragma("unroll") for (int n = 0; n < 2; ++n) _Pragma("unroll") for (int k = 0; k < 2; ++k) \
;         acc[ai][bj][m][n] = __builtin_amdgcn_mfma_f32_16x16x32_bf16(Bt[n][k], At[m][k], acc[ai][bj][m][n], 0, 0, 0); __builtin_amdgcn_s_setprio(0); } while (0)
; #define PG8_WAIT_V(n) asm volatile("s_waitcnt vmcnt(" #n ")" ::: "memory")
; #define PG8_WAIT_L(n) asm volatile("s_waitcnt lgkmcnt(" #n ")" ::: "memory")
; #define PG8_BAR __builtin_amdgcn_s_barrier()
; #define PG8_SCHED __builtin_amdgcn_sched_barrier(0)
; template <class Epi, class Sched, bool ALIGN_EPI = false, bool SP2 = false>
; __device__ __forceinline__ void gemm_phase(PG8_LAS unsigned char* lds, const Gemm g, const Sched& S, const Epi& E) {
;     ...
;             PG8_LDA(At, 1, 1); PG8_STAGE(PG8_SB(1, 0), b3, voffB); PG8_STAGE(PG8_SB(1, 1), b3 + hstep, voffB); PG8_STAGE(PG8_SA(1, 0), a3, voffA);
;             PG8_WAIT_V(8); PG8_WAIT_L(0); PG8_BAR; PG8_MMA(1, 0, At, B0); PG8_MMA(1, 1, At, B1); PG8_BAR; PG8_SCHED;
	s_add_i32 s38, s54, s40
	v_lshl_add_u64 v[162:163], v[162:163], 0, s[10:11]
	s_mov_b32 m0, s38
	ds_read_b128 v[202:205], v173 offset:49152
	ds_read_b128 v[206:209], v173 offset:50176
	ds_read_b128 v[210:213], v173 offset:51200
	ds_read_b128 v[214:217], v173 offset:52224
	ds_read_b128 v[218:221], v173 offset:53248
	ds_read_b128 v[222:225], v173 offset:54272
	ds_read_b128 v[226:229], v173 offset:55296
	ds_read_b128 v[230:233], v173 offset:56320
	global_load_lds_dwordx4 v[162:163], off
	s_add_i32 m0, s38, 0x2000
	s_add_u32 s36, s36, 0x40080
	v_lshl_add_u64 v[162:163], v[192:193], 0, s[10:11]
	s_addc_u32 s37, s37, 0
	s_add_i32 s38, s55, s40
	global_load_lds_dwordx4 v[162:163], off
	v_lshl_add_u64 v[162:163], s[36:37], 0, v[134:135]
	s_mov_b32 m0, s38
	s_nop 0
	global_load_lds_dwordx4 v[162:163], off
	v_lshl_add_u64 v[162:163], s[36:37], 0, v[138:139]
	s_add_i32 m0, s38, 0x2000
	s_nop 0
	global_load_lds_dwordx4 v[162:163], off
	v_lshl_add_u64 v[162:163], v[196:197], 0, s[10:11]
	s_mov_b32 m0, s45
	s_nop 0
	global_load_lds_dwordx4 v[162:163], off
	v_lshl_add_u64 v[162:163], v[234:235], 0, s[10:11]
	s_mov_b32 m0, s46
	s_nop 0
	global_load_lds_dwordx4 v[162:163], off
	s_waitcnt vmcnt(8)
	s_waitcnt lgkmcnt(0)
	s_barrier
	s_setprio 1
	s_waitcnt lgkmcnt(0)
	v_mfma_f32_16x16x32_bf16 v[60:63], v[128:131], v[202:205], v[60:63]
	v_mfma_f32_16x16x32_bf16 v[56:59], v[154:157], v[202:205], v[56:59]
	v_mfma_f32_16x16x32_bf16 v[44:47], v[128:131], v[210:213], v[44:47]
	v_mfma_f32_16x16x32_bf16 v[40:43], v[154:157], v[210:213], v[40:43]
	v_mfma_f32_16x16x32_bf16 v[28:31], v[128:131], v[218:221], v[28:31]
	v_mfma_f32_16x16x32_bf16 v[24:27], v[154:157], v[218:221], v[24:27]
	v_mfma_f32_16x16x32_bf16 v[12:15], v[128:131], v[226:229], v[12:15]
	v_mfma_f32_16x16x32_bf16 v[8:11], v[154:157], v[226:229], v[8:11]
	v_mfma_f32_16x16x32_bf16 v[60:63], v[150:153], v[206:209], v[60:63]
	v_mfma_f32_16x16x32_bf16 v[56:59], v[158:161], v[206:209], v[56:59]
	v_mfma_f32_16x16x32_bf16 v[44:47], v[150:153], v[214:217], v[44:47]
	v_mfma_f32_16x16x32_bf16 v[40:43], v[158:161], v[214:217], v[40:43]
	v_mfma_f32_16x16x32_bf16 v[28:31], v[150:153], v[222:225], v[28:31]
	v_mfma_f32_16x16x32_bf16 v[24:27], v[158:161], v[222:225], v[24:27]
	v_mfma_f32_16x16x32_bf16 v[12:15], v[150:153], v[230:233], v[12:15]
	v_mfma_f32_16x16x32_bf16 v[8:11], v[158:161], v[230:233], v[8:11]
	v_mfma_f32_16x16x32_bf16 v[52:55], v[176:179], v[202:205], v[52:55]
	v_mfma_f32_16x16x32_bf16 v[48:51], v[184:187], v[202:205], v[48:51]
	v_mfma_f32_16x16x32_bf16 v[36:39], v[176:179], v[210:213], v[36:39]
	v_mfma_f32_16x16x32_bf16 v[32:35], v[184:187], v[210:213], v[32:35]
	v_mfma_f32_16x16x32_bf16 v[20:23], v[176:179], v[218:221], v[20:23]
	v_mfma_f32_16x16x32_bf16 v[16:19], v[184:187], v[218:221], v[16:19]
	v_mfma_f32_16x16x32_bf16 v[4:7], v[176:179], v[226:229], v[4:7]
	v_mfma_f32_16x16x32_bf16 v[0:3], v[184:187], v[226:229], v[0:3]
	v_mfma_f32_16x16x32_bf16 v[52:55], v[180:183], v[206:209], v[52:55]
	v_mfma_f32_16x16x32_bf16 v[48:51], v[188:191], v[206:209], v[48:51]
	v_mfma_f32_16x16x32_bf16 v[36:39], v[180:183], v[214:217], v[36:39]
	v_mfma_f32_16x16x32_bf16 v[32:35], v[188:191], v[214:217], v[32:35]
	v_mfma_f32_16x16x32_bf16 v[20:23], v[180:183], v[222:225], v[20:23]
	v_mfma_f32_16x16x32_bf16 v[16:19], v[188:191], v[222:225], v[16:19]
	v_mfma_f32_16x16x32_bf16 v[4:7], v[180:183], v[230:233], v[4:7]
	v_mfma_f32_16x16x32_bf16 v[0:3], v[188:191], v[230:233], v[0:3]
	s_setprio 0
	s_barrier
	s_add_i32 s53, s53, 2
	s_add_u32 s0, s0, 0x100
	s_addc_u32 s1, s1, 0
	s_add_u32 s51, s51, 0x100
	s_addc_u32 s52, s52, 0
	s_cmp_gt_u32 s53, 13
	s_cbranch_scc0 .LBB0_369
	s_and_b64 vcc, exec, s[12:13]
	s_cbranch_vccz .LBB0_372
	s_barrier

; #define PG8_STAGE(bufoff, gbase, voff) do { _Pragma("unroll") for (int _i = 0; _i < 2; ++_i) \
;         __builtin_amdgcn_global_load_lds((const unsigned*)((const char*)(gbase) + (voff)[_i]), (PG8_LAS unsigned*)(lds + (bufoff) + ldsw + _i * 8192), 16, 0, 0); } while (0)
; #define PG8_LDA(dst, b, h) do { _Pragma("unroll") for (int m = 0; m < 4; ++m) _Pragma("unroll") for (int k = 0; k < 2; ++k) dst[m][k] = *(const PG8_LAS bf16x8*)(lds + PG8_SA(b, h) + aoff + m * 2048 + k * 1024); } while (0)
; #define PG8_LDB(dst, b, h) do { _Pragma("unroll") for (int n = 0; n < 2; ++n) _Pragma("unroll") for (int k = 0; k < 2; ++k) dst[n][k] = *(const PG8_LAS bf16x8*)(lds + PG8_SB(b, h) + boff + n * 2048 + k * 1024); } while (0)
; #define PG8_MMA(ai, bj, At, Bt) do { __builtin_amdgcn_s_setprio(1); _Pragma("unroll") for (int m = 0; m < 4; ++m) _Pragma("unroll") for (int n = 0; n < 2; ++n) _Pragma("unroll") for (int k = 0; k < 2; ++k) \
;         acc[ai][bj][m][n] = __builtin_amdgcn_mfma_f32_16x16x32_bf16(Bt[n][k], At[m][k], acc[ai][bj][m][n], 0, 0, 0); __builtin_amdgcn_s_setprio(0); } while (0)
; #define PG8_WAIT_V(n) asm volatile("s_waitcnt vmcnt(" #n ")" ::: "memory")
; #define PG8_WAIT_L(n) asm volatile("s_waitcnt lgkmcnt(" #n ")" ::: "memory")
; #define PG8_BAR __builtin_amdgcn_s_barrier()
; #define PG8_SCHED __builtin_amdgcn_sched_barrier(0)
; template <class Epi, class Sched, bool ALIGN_EPI = false, bool SP2 = false>
; __device__ __forceinline__ void gemm_phase(PG8_LAS unsigned char* lds, const Gemm g, const Sched& S, const Epi& E) {
;     ...
;             const bool last = (t == nt - 2);
;             const char* a1 = cA + (size_t)(t + 1) * kstep;
;             const char* a2 = last ? nA : cA + (size_t)(t + 2) * kstep; const char* b2 = last ? nB : cB + (size_t)(t + 2) * kstep;
;             const char* a3 = a2 + kstep; const char* b3 = b2 + kstep;
;             if (last && has_next) S.a_ready(nxt);
;             if constexpr (SP2) {
;             PG8_LDB(B0, 0, 0); PG8_LDB(B1, 0, 1); PG8_SCHED; PG8_LDA(At, 0, 0); PG8_STAGE(PG8_SA(1, 1), a1 + hstep, voffA);
;             PG8_WAIT_V(8); PG8_WAIT_L(0); PG8_BAR; PG8_MMA(0, 0, At, B0); PG8_MMA(0, 1, At, B1); PG8_BAR; PG8_SCHED;
;             PG8_LDA(At, 0, 1); PG8_STAGE(PG8_SB(0, 0), b2, voffB); PG8_STAGE(PG8_SB(0, 1), b2 + hstep, voffB); PG8_STAGE(PG8_SA(0, 0), a2, voffA);
.LBB0_699:
	ds_read_b128 v[128:131], v222
	ds_read_b128 v[132:135], v222 offset:1024
	ds_read_b128 v[136:139], v222 offset:2048
	ds_read_b128 v[140:143], v222 offset:3072
	ds_read_b128 v[144:147], v223
	ds_read_b128 v[148:151], v223 offset:1024
	ds_read_b128 v[152:155], v223 offset:2048
	ds_read_b128 v[156:159], v223 offset:3072
	s_add_u32 s34, s0, 0xfffc0080
	s_addc_u32 s35, s1, -1
	s_cmp_eq_u32 s65, 12
	s_cselect_b32 s37, s25, s35
	s_cselect_b32 s36, s31, s34
	s_cselect_b32 s35, s23, s63
	s_cselect_b32 s34, s33, s62
	v_lshl_add_u64 v[244:245], s[0:1], 0, v[182:183]
	s_add_i32 m0, s39, 0xc000
	ds_read_b128 v[160:163], v224
	ds_read_b128 v[164:167], v224 offset:1024
	ds_read_b128 v[190:193], v224 offset:2048
	ds_read_b128 v[194:197], v224 offset:3072
	ds_read_b128 v[228:231], v224 offset:4096
	ds_read_b128 v[232:235], v224 offset:5120
	ds_read_b128 v[236:239], v224 offset:6144
	ds_read_b128 v[240:243], v224 offset:7168
	global_load_lds_dwordx4 v[244:245], off
	v_lshl_add_u64 v[244:245], s[0:1], 0, v[184:185]
	s_add_i32 m0, s39, 0xe000
	s_nop 0
	global_load_lds_dwordx4 v[244:245], off
	s_waitcnt vmcnt(8)
	s_waitcnt lgkmcnt(0)
	s_barrier
	s_setprio 1
	s_waitcnt lgkmcnt(0)
	v_mfma_f32_16x16x32_bf16 v[124:127], v[128:131], v[160:163], v[124:127]
	v_mfma_f32_16x16x32_bf16 v[120:123], v[136:139], v[160:163], v[120:123]
	v_mfma_f32_16x16x32_bf16 v[108:111], v[128:131], v[190:193], v[108:111]
	v_mfma_f32_16x16x32_bf16 v[104:107], v[136:139], v[190:193], v[104:107]
	v_mfma_f32_16x16x32_bf16 v[92:95], v[128:131], v[228:231], v[92:95]
	v_mfma_f32_16x16x32_bf16 v[88:91], v[136:139], v[228:231], v[88:91]
	v_mfma_f32_16x16x32_bf16 v[76:79], v[128:131], v[236:239], v[76:79]
	v_mfma_f32_16x16x32_bf16 v[72:75], v[136:139], v[236:239], v[72:75]
	v_mfma_f32_16x16x32_bf16 v[124:127], v[132:135], v[164:167], v[124:127]
	v_mfma_f32_16x16x32_bf16 v[120:123], v[140:143], v[164:167], v[120:123]
	v_mfma_f32_16x16x32_bf16 v[108:111], v[132:135], v[194:197], v[108:111]
	v_mfma_f32_16x16x32_bf16 v[104:107], v[140:143], v[194:197], v[104:107]
	v_mfma_f32_16x16x32_bf16 v[92:95], v[132:135], v[232:235], v[92:95]
	v_mfma_f32_16x16x32_bf16 v[88:91], v[140:143], v[232:235], v[88:91]
	v_mfma_f32_16x16x32_bf16 v[76:79], v[132:135], v[240:243], v[76:79]
	v_mfma_f32_16x16x32_bf16 v[72:75], v[140:143], v[240:243], v[72:75]
	v_mfma_f32_16x16x32_bf16 v[116:119], v[144:147], v[160:163], v[116:119]
	v_mfma_f32_16x16x32_bf16 v[112:115], v[152:155], v[160:163], v[112:115]
	v_mfma_f32_16x16x32_bf16 v[100:103], v[144:147], v[190:193], v[100:103]
	v_mfma_f32_16x16x32_bf16 v[96:99], v[152:155], v[190:193], v[96:99]
	v_mfma_f32_16x16x32_bf16 v[84:87], v[144:147], v[228:231], v[84:87]
	v_mfma_f32_16x16x32_bf16 v[80:83], v[152:155], v[228:231], v[80:83]
	v_mfma_f32_16x16x32_bf16 v[68:71], v[144:147], v[236:239], v[68:71]
	v_mfma_f32_16x16x32_bf16 v[64:67], v[152:155], v[236:239], v[64:67]
	v_mfma_f32_16x16x32_bf16 v[116:119], v[148:151], v[164:167], v[116:119]
	v_mfma_f32_16x16x32_bf16 v[112:115], v[156:159], v[164:167], v[112:115]
	v_mfma_f32_16x16x32_bf16 v[100:103], v[148:151], v[194:197], v[100:103]
	v_mfma_f32_16x16x32_bf16 v[96:99], v[156:159], v[194:197], v[96:99]
	v_mfma_f32_16x16x32_bf16 v[84:87], v[148:151], v[232:235], v[84:87]
	v_mfma_f32_16x16x32_bf16 v[80:83], v[156:159], v[232:235], v[80:83]
	v_mfma_f32_16x16x32_bf16 v[68:71], v[148:151], v[240:243], v[68:71]
	v_mfma_f32_16x16x32_bf16 v[64:67], v[156:159], v[240:243], v[64:67]
	s_setprio 0
	s_barrier
	s_add_i32 s66, s46, s38
	v_lshl_add_u64 v[244:245], s[34:35], 0, v[174:175]
	s_mov_b32 m0, s66
	ds_read_b128 v[160:163], v224 offset:16384
	ds_read_b128 v[164:167], v224 offset:17408
	ds_read_b128 v[190:193], v224 offset:18432
	ds_read_b128 v[194:197], v224 offset:19456
	ds_read_b128 v[228:231], v224 offset:20480
	ds_read_b128 v[232:235], v224 offset:21504
	ds_read_b128 v[236:239], v224 offset:22528
	ds_read_b128 v[240:243], v224 offset:23552
	global_load_lds_dwordx4 v[244:245], off
	s_add_i32 m0, s66, 0x2000
	s_add_u32 s66, s34, 0x40000
	v_lshl_add_u64 v[246:247], s[34:35], 0, v[178:179]
	s_addc_u32 s67, s35, 0
	s_add_i32 s68, s56, s38
	global_load_lds_dwordx4 v[246:247], off
	v_lshl_add_u64 v[248:249], s[66:67], 0, v[174:175]
	s_mov_b32 m0, s68
	v_lshl_add_u64 v[250:251], s[36:37], 0, v[176:177]
	global_load_lds_dwordx4 v[248:249], off
	v_lshl_add_u64 v[248:249], s[66:67], 0, v[178:179]
	s_add_i32 m0, s68, 0x2000
	s_nop 0
	global_load_lds_dwordx4 v[248:249], off
	v_lshl_add_u64 v[248:249], s[36:37], 0, v[172:173]
	s_mov_b32 m0, s39
	s_nop 0
	global_load_lds_dwordx4 v[248:249], off
	s_mov_b32 m0, s40
	s_nop 0
	global_load_lds_dwordx4 v[250:251], off
	s_waitcnt vmcnt(8)
	s_waitcnt lgkmcnt(0)
	s_barrier
; #define PG8_STAGE(bufoff, gbase, voff) do { _Pragma("unroll") for (int _i = 0; _i < 2; ++_i) \
;         __builtin_amdgcn_global_load_lds((const unsigned*)((const char*)(gbase) + (voff)[_i]), (PG8_LAS unsigned*)(lds + (bufoff) + ldsw + _i * 8192), 16, 0, 0); } while (0)
; #define PG8_LDA(dst, b, h) do { _Pragma("unroll") for (int m = 0; m < 4; ++m) _Pragma("unroll") for (int k = 0; k < 2; ++k) dst[m][k] = *(const PG8_LAS bf16x8*)(lds + PG8_SA(b, h) + aoff + m * 2048 + k * 1024); } while (0)
; #define PG8_LDB(dst, b, h) do { _Pragma("unroll") for (int n = 0; n < 2; ++n) _Pragma("unroll") for (int k = 0; k < 2; ++k) dst[n][k] = *(const PG8_LAS bf16x8*)(lds + PG8_SB(b, h) + boff + n * 2048 + k * 1024); } while (0)
; #define PG8_MMA(ai, bj, At, Bt) do { __builtin_amdgcn_s_setprio(1); _Pragma("unroll") for (int m = 0; m < 4; ++m) _Pragma("unroll") for (int n = 0; n < 2; ++n) _Pragma("unroll") for (int k = 0; k < 2; ++k) \
;         acc[ai][bj][m][n] = __builtin_amdgcn_mfma_f32_16x16x32_bf16(Bt[n][k], At[m][k], acc[ai][bj][m][n], 0, 0, 0); __builtin_amdgcn_s_setprio(0); } while (0)
; #define PG8_WAIT_V(n) asm volatile("s_waitcnt vmcnt(" #n ")" ::: "memory")
; #define PG8_WAIT_L(n) asm volatile("s_waitcnt lgkmcnt(" #n ")" ::: "memory")
; #define PG8_BAR __builtin_amdgcn_s_barrier()
; #define PG8_SCHED __builtin_amdgcn_sched_barrier(0)
; template <class Epi, class Sched, bool ALIGN_EPI = false, bool SP2 = false>
; __device__ __forceinline__ void gemm_phase(PG8_LAS unsigned char* lds, const Gemm g, const Sched& S, const Epi& E) {
;     ...
;             PG8_WAIT_V(8); PG8_WAIT_L(0); PG8_BAR; PG8_MMA(1, 0, At, B0); PG8_MMA(1, 1, At, B1); PG8_BAR; PG8_SCHED;
;             PG8_LDB(B0, 1, 0); PG8_LDB(B1, 1, 1); PG8_SCHED; PG8_LDA(At, 1, 0); PG8_STAGE(PG8_SA(0, 1), a2 + hstep, voffA);
;             PG8_WAIT_V(8); PG8_WAIT_L(0); PG8_BAR; PG8_MMA(0, 0, At, B0); PG8_MMA(0, 1, At, B1); PG8_BAR; PG8_SCHED;
	s_setprio 1
	s_waitcnt lgkmcnt(0)
	v_mfma_f32_16x16x32_bf16 v[60:63], v[128:131], v[160:163], v[60:63]
	v_mfma_f32_16x16x32_bf16 v[56:59], v[136:139], v[160:163], v[56:59]
	v_mfma_f32_16x16x32_bf16 v[44:47], v[128:131], v[190:193], v[44:47]
	v_mfma_f32_16x16x32_bf16 v[40:43], v[136:139], v[190:193], v[40:43]
	v_mfma_f32_16x16x32_bf16 v[28:31], v[128:131], v[228:231], v[28:31]
	v_mfma_f32_16x16x32_bf16 v[24:27], v[136:139], v[228:231], v[24:27]
	v_mfma_f32_16x16x32_bf16 v[12:15], v[128:131], v[236:239], v[12:15]
	v_mfma_f32_16x16x32_bf16 v[8:11], v[136:139], v[236:239], v[8:11]
	v_mfma_f32_16x16x32_bf16 v[60:63], v[132:135], v[164:167], v[60:63]
	v_mfma_f32_16x16x32_bf16 v[56:59], v[140:143], v[164:167], v[56:59]
	v_mfma_f32_16x16x32_bf16 v[44:47], v[132:135], v[194:197], v[44:47]
	v_mfma_f32_16x16x32_bf16 v[40:43], v[140:143], v[194:197], v[40:43]
	v_mfma_f32_16x16x32_bf16 v[28:31], v[132:135], v[232:235], v[28:31]
	v_mfma_f32_16x16x32_bf16 v[24:27], v[140:143], v[232:235], v[24:27]
	v_mfma_f32_16x16x32_bf16 v[12:15], v[132:135], v[240:243], v[12:15]
	v_mfma_f32_16x16x32_bf16 v[8:11], v[140:143], v[240:243], v[8:11]
	v_mfma_f32_16x16x32_bf16 v[52:55], v[144:147], v[160:163], v[52:55]
	v_mfma_f32_16x16x32_bf16 v[48:51], v[152:155], v[160:163], v[48:51]
	v_mfma_f32_16x16x32_bf16 v[36:39], v[144:147], v[190:193], v[36:39]
	v_mfma_f32_16x16x32_bf16 v[32:35], v[152:155], v[190:193], v[32:35]
	v_mfma_f32_16x16x32_bf16 v[20:23], v[144:147], v[228:231], v[20:23]
	v_mfma_f32_16x16x32_bf16 v[16:19], v[152:155], v[228:231], v[16:19]
	v_mfma_f32_16x16x32_bf16 v[4:7], v[144:147], v[236:239], v[4:7]
	v_mfma_f32_16x16x32_bf16 v[0:3], v[152:155], v[236:239], v[0:3]
	v_mfma_f32_16x16x32_bf16 v[52:55], v[148:151], v[164:167], v[52:55]
	v_mfma_f32_16x16x32_bf16 v[48:51], v[156:159], v[164:167], v[48:51]
	v_mfma_f32_16x16x32_bf16 v[36:39], v[148:151], v[194:197], v[36:39]
	v_mfma_f32_16x16x32_bf16 v[32:35], v[156:159], v[194:197], v[32:35]
	v_mfma_f32_16x16x32_bf16 v[20:23], v[148:151], v[232:235], v[20:23]
	v_mfma_f32_16x16x32_bf16 v[16:19], v[156:159], v[232:235], v[16:19]
	v_mfma_f32_16x16x32_bf16 v[4:7], v[148:151], v[240:243], v[4:7]
	v_mfma_f32_16x16x32_bf16 v[0:3], v[156:159], v[240:243], v[0:3]
	s_setprio 0
	s_barrier
	s_add_i32 s66, 0, 0x18000
	s_add_i32 s67, 0, 0x1c000
	v_add_u32_e32 v140, s66, v204
	v_add_u32_e32 v156, s67, v204
	ds_read_b128 v[128:131], v140
	ds_read_b128 v[132:135], v140 offset:1024
	ds_read_b128 v[136:139], v140 offset:2048
	ds_read_b128 v[140:143], v140 offset:3072
	ds_read_b128 v[144:147], v156
	ds_read_b128 v[148:151], v156 offset:1024
	ds_read_b128 v[152:155], v156 offset:2048
	ds_read_b128 v[156:159], v156 offset:3072
	s_add_u32 s36, s36, 0x40000
	s_addc_u32 s37, s37, 0
	s_mov_b32 m0, s41
	v_lshl_add_u64 v[252:253], s[36:37], 0, v[172:173]
	ds_read_b128 v[160:163], v224 offset:32768
	ds_read_b128 v[164:167], v224 offset:33792
	ds_read_b128 v[190:193], v224 offset:34816
	ds_read_b128 v[194:197], v224 offset:35840
	ds_read_b128 v[228:231], v224 offset:36864
	ds_read_b128 v[232:235], v224 offset:37888
	ds_read_b128 v[236:239], v224 offset:38912
	ds_read_b128 v[240:243], v224 offset:39936
	global_load_lds_dwordx4 v[252:253], off
	v_lshl_add_u64 v[252:253], s[36:37], 0, v[176:177]
	s_mov_b32 m0, s42
	s_nop 0
	global_load_lds_dwordx4 v[252:253], off
	s_waitcnt vmcnt(8)
	s_waitcnt lgkmcnt(0)
	s_barrier
	s_setprio 1
	s_waitcnt lgkmcnt(0)
	v_mfma_f32_16x16x32_bf16 v[124:127], v[128:131], v[160:163], v[124:127]
	v_mfma_f32_16x16x32_bf16 v[120:123], v[136:139], v[160:163], v[120:123]
	v_mfma_f32_16x16x32_bf16 v[108:111], v[128:131], v[190:193], v[108:111]
	v_mfma_f32_16x16x32_bf16 v[104:107], v[136:139], v[190:193], v[104:107]
	v_mfma_f32_16x16x32_bf16 v[92:95], v[128:131], v[228:231], v[92:95]
	v_mfma_f32_16x16x32_bf16 v[88:91], v[136:139], v[228:231], v[88:91]
	v_mfma_f32_16x16x32_bf16 v[76:79], v[128:131], v[236:239], v[76:79]
	v_mfma_f32_16x16x32_bf16 v[72:75], v[136:139], v[236:239], v[72:75]
	v_mfma_f32_16x16x32_bf16 v[124:127], v[132:135], v[164:167], v[124:127]
	v_mfma_f32_16x16x32_bf16 v[120:123], v[140:143], v[164:167], v[120:123]
	v_mfma_f32_16x16x32_bf16 v[108:111], v[132:135], v[194:197], v[108:111]
	v_mfma_f32_16x16x32_bf16 v[104:107], v[140:143], v[194:197], v[104:107]
	v_mfma_f32_16x16x32_bf16 v[92:95], v[132:135], v[232:235], v[92:95]
	v_mfma_f32_16x16x32_bf16 v[88:91], v[140:143], v[232:235], v[88:91]
	v_mfma_f32_16x16x32_bf16 v[76:79], v[132:135], v[240:243], v[76:79]
	v_mfma_f32_16x16x32_bf16 v[72:75], v[140:143], v[240:243], v[72:75]
	v_mfma_f32_16x16x32_bf16 v[116:119], v[144:147], v[160:163], v[116:119]
	v_mfma_f32_16x16x32_bf16 v[112:115], v[152:155], v[160:163], v[112:115]
	v_mfma_f32_16x16x32_bf16 v[100:103], v[144:147], v[190:193], v[100:103]
	v_mfma_f32_16x16x32_bf16 v[96:99], v[152:155], v[190:193], v[96:99]
	v_mfma_f32_16x16x32_bf16 v[84:87], v[144:147], v[228:231], v[84:87]
	v_mfma_f32_16x16x32_bf16 v[80:83], v[152:155], v[228:231], v[80:83]
	v_mfma_f32_16x16x32_bf16 v[68:71], v[144:147], v[236:239], v[68:71]
	v_mfma_f32_16x16x32_bf16 v[64:67], v[152:155], v[236:239], v[64:67]
	v_mfma_f32_16x16x32_bf16 v[116:119], v[148:151], v[164:167], v[116:119]
	v_mfma_f32_16x16x32_bf16 v[112:115], v[156:159], v[164:167], v[112:115]
	v_mfma_f32_16x16x32_bf16 v[100:103], v[148:151], v[194:197], v[100:103]
	v_mfma_f32_16x16x32_bf16 v[96:99], v[156:159], v[194:197], v[96:99]
	v_mfma_f32_16x16x32_bf16 v[84:87], v[148:151], v[232:235], v[84:87]
	v_mfma_f32_16x16x32_bf16 v[80:83], v[156:159], v[232:235], v[80:83]
	v_mfma_f32_16x16x32_bf16 v[68:71], v[148:151], v[240:243], v[68:71]
	v_mfma_f32_16x16x32_bf16 v[64:67], v[156:159], v[240:243], v[64:67]
	s_setprio 0
	s_barrier
; #define PG8_STAGE(bufoff, gbase, voff) do { _Pragma("unroll") for (int _i = 0; _i < 2; ++_i) \
;         __builtin_amdgcn_global_load_lds((const unsigned*)((const char*)(gbase) + (voff)[_i]), (PG8_LAS unsigned*)(lds + (bufoff) + ldsw + _i * 8192), 16, 0, 0); } while (0)
; #define PG8_LDA(dst, b, h) do { _Pragma("unroll") for (int m = 0; m < 4; ++m) _Pragma("unroll") for (int k = 0; k < 2; ++k) dst[m][k] = *(const PG8_LAS bf16x8*)(lds + PG8_SA(b, h) + aoff + m * 2048 + k * 1024); } while (0)
; #define PG8_MMA(ai, bj, At, Bt) do { __builtin_amdgcn_s_setprio(1); _Pragma("unroll") for (int m = 0; m < 4; ++m) _Pragma("unroll") for (int n = 0; n < 2; ++n) _Pragma("unroll") for (int k = 0; k < 2; ++k) \
;         acc[ai][bj][m][n] = __builtin_amdgcn_mfma_f32_16x16x32_bf16(Bt[n][k], At[m][k], acc[ai][bj][m][n], 0, 0, 0); __builtin_amdgcn_s_setprio(0); } while (0)
; #define PG8_WAIT_V(n) asm volatile("s_waitcnt vmcnt(" #n ")" ::: "memory")
; #define PG8_WAIT_L(n) asm volatile("s_waitcnt lgkmcnt(" #n ")" ::: "memory")
; #define PG8_BAR __builtin_amdgcn_s_barrier()
; #define PG8_SCHED __builtin_amdgcn_sched_barrier(0)
; template <class Epi, class Sched, bool ALIGN_EPI = false, bool SP2 = false>
; __device__ __forceinline__ void gemm_phase(PG8_LAS unsigned char* lds, const Gemm g, const Sched& S, const Epi& E) {
;     ...
;             PG8_LDA(At, 1, 1); PG8_STAGE(PG8_SB(1, 0), b3, voffB); PG8_STAGE(PG8_SB(1, 1), b3 + hstep, voffB); PG8_STAGE(PG8_SA(1, 0), a3, voffA);
;             PG8_WAIT_V(8); PG8_WAIT_L(0); PG8_BAR; PG8_MMA(1, 0, At, B0); PG8_MMA(1, 1, At, B1); PG8_BAR; PG8_SCHED;
	s_add_i32 s36, s66, s38
	v_lshl_add_u64 v[244:245], v[244:245], 0, s[16:17]
	s_mov_b32 m0, s36
	ds_read_b128 v[160:163], v224 offset:49152
	ds_read_b128 v[164:167], v224 offset:50176
	ds_read_b128 v[190:193], v224 offset:51200
	ds_read_b128 v[194:197], v224 offset:52224
	ds_read_b128 v[228:231], v224 offset:53248
	ds_read_b128 v[232:235], v224 offset:54272
	ds_read_b128 v[236:239], v224 offset:55296
	ds_read_b128 v[240:243], v224 offset:56320
	global_load_lds_dwordx4 v[244:245], off
	s_add_i32 m0, s36, 0x2000
	s_add_u32 s34, s34, 0x40080
	v_lshl_add_u64 v[244:245], v[246:247], 0, s[16:17]
	s_addc_u32 s35, s35, 0
	s_add_i32 s36, s67, s38
	global_load_lds_dwordx4 v[244:245], off
	v_lshl_add_u64 v[244:245], s[34:35], 0, v[174:175]
	s_mov_b32 m0, s36
	s_nop 0
	global_load_lds_dwordx4 v[244:245], off
	v_lshl_add_u64 v[244:245], s[34:35], 0, v[178:179]
	s_add_i32 m0, s36, 0x2000
	s_nop 0
	global_load_lds_dwordx4 v[244:245], off
	v_lshl_add_u64 v[244:245], v[248:249], 0, s[16:17]
	s_mov_b32 m0, s50
	s_nop 0
	global_load_lds_dwordx4 v[244:245], off
	v_lshl_add_u64 v[244:245], v[250:251], 0, s[16:17]
	s_mov_b32 m0, s51
	s_nop 0
	global_load_lds_dwordx4 v[244:245], off
	s_waitcnt vmcnt(8)
	s_waitcnt lgkmcnt(0)
	s_barrier
	s_setprio 1
	s_waitcnt lgkmcnt(0)
	v_mfma_f32_16x16x32_bf16 v[60:63], v[128:131], v[160:163], v[60:63]
	v_mfma_f32_16x16x32_bf16 v[56:59], v[136:139], v[160:163], v[56:59]
	v_mfma_f32_16x16x32_bf16 v[44:47], v[128:131], v[190:193], v[44:47]
	v_mfma_f32_16x16x32_bf16 v[40:43], v[136:139], v[190:193], v[40:43]
	v_mfma_f32_16x16x32_bf16 v[28:31], v[128:131], v[228:231], v[28:31]
	v_mfma_f32_16x16x32_bf16 v[24:27], v[136:139], v[228:231], v[24:27]
	v_mfma_f32_16x16x32_bf16 v[12:15], v[128:131], v[236:239], v[12:15]
	v_mfma_f32_16x16x32_bf16 v[8:11], v[136:139], v[236:239], v[8:11]
	v_mfma_f32_16x16x32_bf16 v[60:63], v[132:135], v[164:167], v[60:63]
	v_mfma_f32_16x16x32_bf16 v[56:59], v[140:143], v[164:167], v[56:59]
	v_mfma_f32_16x16x32_bf16 v[44:47], v[132:135], v[194:197], v[44:47]
	v_mfma_f32_16x16x32_bf16 v[40:43], v[140:143], v[194:197], v[40:43]
	v_mfma_f32_16x16x32_bf16 v[28:31], v[132:135], v[232:235], v[28:31]
	v_mfma_f32_16x16x32_bf16 v[24:27], v[140:143], v[232:235], v[24:27]
	v_mfma_f32_16x16x32_bf16 v[12:15], v[132:135], v[240:243], v[12:15]
	v_mfma_f32_16x16x32_bf16 v[8:11], v[140:143], v[240:243], v[8:11]
	v_mfma_f32_16x16x32_bf16 v[52:55], v[144:147], v[160:163], v[52:55]
	v_mfma_f32_16x16x32_bf16 v[48:51], v[152:155], v[160:163], v[48:51]
	v_mfma_f32_16x16x32_bf16 v[36:39], v[144:147], v[190:193], v[36:39]
	v_mfma_f32_16x16x32_bf16 v[32:35], v[152:155], v[190:193], v[32:35]
	v_mfma_f32_16x16x32_bf16 v[20:23], v[144:147], v[228:231], v[20:23]
	v_mfma_f32_16x16x32_bf16 v[16:19], v[152:155], v[228:231], v[16:19]
	v_mfma_f32_16x16x32_bf16 v[4:7], v[144:147], v[236:239], v[4:7]
	v_mfma_f32_16x16x32_bf16 v[0:3], v[152:155], v[236:239], v[0:3]
	v_mfma_f32_16x16x32_bf16 v[52:55], v[148:151], v[164:167], v[52:55]
	v_mfma_f32_16x16x32_bf16 v[48:51], v[156:159], v[164:167], v[48:51]
	v_mfma_f32_16x16x32_bf16 v[36:39], v[148:151], v[194:197], v[36:39]
	v_mfma_f32_16x16x32_bf16 v[32:35], v[156:159], v[194:197], v[32:35]
	v_mfma_f32_16x16x32_bf16 v[20:23], v[148:151], v[232:235], v[20:23]
	v_mfma_f32_16x16x32_bf16 v[16:19], v[156:159], v[232:235], v[16:19]
	v_mfma_f32_16x16x32_bf16 v[4:7], v[148:151], v[240:243], v[4:7]
	v_mfma_f32_16x16x32_bf16 v[0:3], v[156:159], v[240:243], v[0:3]
	s_setprio 0
	s_barrier
	s_add_i32 s65, s65, 2
	s_add_u32 s0, s0, 0x100
	s_addc_u32 s1, s1, 0
	s_add_u32 s62, s62, 0x100
	s_addc_u32 s63, s63, 0
	s_cmp_gt_u32 s65, 13
	s_cbranch_scc0 .LBB0_699
	s_and_b64 vcc, exec, s[18:19]
	s_cbranch_vccz .LBB0_702
	s_barrier

; #define PG8_STAGE(bufoff, gbase, voff) do { _Pragma("unroll") for (int _i = 0; _i < 2; ++_i) \
;         __builtin_amdgcn_global_load_lds((const unsigned*)((const char*)(gbase) + (voff)[_i]), (PG8_LAS unsigned*)(lds + (bufoff) + ldsw + _i * 8192), 16, 0, 0); } while (0)
; #define PG8_LDA(dst, b, h) do { _Pragma("unroll") for (int m = 0; m < 4; ++m) _Pragma("unroll") for (int k = 0; k < 2; ++k) dst[m][k] = *(const PG8_LAS bf16x8*)(lds + PG8_SA(b, h) + aoff + m * 2048 + k * 1024); } while (0)
; #define PG8_LDB(dst, b, h) do { _Pragma("unroll") for (int n = 0; n < 2; ++n) _Pragma("unroll") for (int k = 0; k < 2; ++k) dst[n][k] = *(const PG8_LAS bf16x8*)(lds + PG8_SB(b, h) + boff + n * 2048 + k * 1024); } while (0)
; #define PG8_MMA(ai, bj, At, Bt) do { __builtin_amdgcn_s_setprio(1); _Pragma("unroll") for (int m = 0; m < 4; ++m) _Pragma("unroll") for (int n = 0; n < 2; ++n) _Pragma("unroll") for (int k = 0; k < 2; ++k) \
;         acc[ai][bj][m][n] = __builtin_amdgcn_mfma_f32_16x16x32_bf16(Bt[n][k], At[m][k], acc[ai][bj][m][n], 0, 0, 0); __builtin_amdgcn_s_setprio(0); } while (0)
; #define PG8_WAIT_V(n) asm volatile("s_waitcnt vmcnt(" #n ")" ::: "memory")
; #define PG8_WAIT_L(n) asm volatile("s_waitcnt lgkmcnt(" #n ")" ::: "memory")
; #define PG8_BAR __builtin_amdgcn_s_barrier()
; #define PG8_SCHED __builtin_amdgcn_sched_barrier(0)
; template <class Epi, class Sched, bool ALIGN_EPI = false, bool SP2 = false>
; __device__ __forceinline__ void gemm_phase(PG8_LAS unsigned char* lds, const Gemm g, const Sched& S, const Epi& E) {
;     ...
;             const bool last = (t == nt - 2);
;             const char* a1 = cA + (size_t)(t + 1) * kstep;
;             const char* a2 = last ? nA : cA + (size_t)(t + 2) * kstep; const char* b2 = last ? nB : cB + (size_t)(t + 2) * kstep;
;             const char* a3 = a2 + kstep; const char* b3 = b2 + kstep;
;             if (last && has_next) S.a_ready(nxt);
;             if constexpr (SP2) {
;             PG8_LDB(B0, 0, 0); PG8_LDB(B1, 0, 1); PG8_SCHED; PG8_LDA(At, 0, 0); PG8_STAGE(PG8_SA(1, 1), a1 + hstep, voffA);
;             PG8_WAIT_V(8); PG8_WAIT_L(0); PG8_BAR; PG8_MMA(0, 0, At, B0); PG8_MMA(0, 1, At, B1); PG8_BAR; PG8_SCHED;
;             PG8_LDA(At, 0, 1); PG8_STAGE(PG8_SB(0, 0), b2, voffB); PG8_STAGE(PG8_SB(0, 1), b2 + hstep, voffB); PG8_STAGE(PG8_SA(0, 0), a2, voffA);
.LBB0_826:
	ds_read_b128 v[154:157], v150
	ds_read_b128 v[158:161], v150 offset:1024
	ds_read_b128 v[162:165], v150 offset:2048
	ds_read_b128 v[170:173], v150 offset:3072
	ds_read_b128 v[174:177], v151
	ds_read_b128 v[178:181], v151 offset:1024
	ds_read_b128 v[182:185], v151 offset:2048
	ds_read_b128 v[186:189], v151 offset:3072
	s_add_u32 s22, s0, 0xfffc0080
	s_addc_u32 s23, s1, -1
	s_cmp_eq_u32 s44, 12
	s_cselect_b32 s25, s15, s23
	s_cselect_b32 s24, s40, s22
	s_cselect_b32 s23, s13, s43
	s_cselect_b32 s22, s41, s42
	v_lshl_add_u64 v[144:145], s[0:1], 0, v[136:137]
	s_add_i32 m0, s21, 0xc000
	ds_read_b128 v[190:193], v152
	ds_read_b128 v[194:197], v152 offset:1024
	ds_read_b128 v[204:207], v152 offset:2048
	ds_read_b128 v[208:211], v152 offset:3072
	ds_read_b128 v[212:215], v152 offset:4096
	ds_read_b128 v[216:219], v152 offset:5120
	ds_read_b128 v[220:223], v152 offset:6144
	ds_read_b128 v[224:227], v152 offset:7168
	global_load_lds_dwordx4 v[144:145], off
	v_lshl_add_u64 v[144:145], s[0:1], 0, v[138:139]
	s_add_i32 m0, s21, 0xe000
	s_nop 0
	global_load_lds_dwordx4 v[144:145], off
	s_waitcnt vmcnt(8)
	s_waitcnt lgkmcnt(0)
	s_barrier
	s_setprio 1
	s_waitcnt lgkmcnt(0)
	v_mfma_f32_16x16x32_bf16 v[124:127], v[154:157], v[190:193], v[124:127]
	v_mfma_f32_16x16x32_bf16 v[120:123], v[162:165], v[190:193], v[120:123]
	v_mfma_f32_16x16x32_bf16 v[108:111], v[154:157], v[204:207], v[108:111]
	v_mfma_f32_16x16x32_bf16 v[104:107], v[162:165], v[204:207], v[104:107]
	v_mfma_f32_16x16x32_bf16 v[92:95], v[154:157], v[212:215], v[92:95]
	v_mfma_f32_16x16x32_bf16 v[88:91], v[162:165], v[212:215], v[88:91]
	v_mfma_f32_16x16x32_bf16 v[76:79], v[154:157], v[220:223], v[76:79]
	v_mfma_f32_16x16x32_bf16 v[72:75], v[162:165], v[220:223], v[72:75]
	v_mfma_f32_16x16x32_bf16 v[124:127], v[158:161], v[194:197], v[124:127]
	v_mfma_f32_16x16x32_bf16 v[120:123], v[170:173], v[194:197], v[120:123]
	v_mfma_f32_16x16x32_bf16 v[108:111], v[158:161], v[208:211], v[108:111]
	v_mfma_f32_16x16x32_bf16 v[104:107], v[170:173], v[208:211], v[104:107]
	v_mfma_f32_16x16x32_bf16 v[92:95], v[158:161], v[216:219], v[92:95]
	v_mfma_f32_16x16x32_bf16 v[88:91], v[170:173], v[216:219], v[88:91]
	v_mfma_f32_16x16x32_bf16 v[76:79], v[158:161], v[224:227], v[76:79]
	v_mfma_f32_16x16x32_bf16 v[72:75], v[170:173], v[224:227], v[72:75]
	v_mfma_f32_16x16x32_bf16 v[116:119], v[174:177], v[190:193], v[116:119]
	v_mfma_f32_16x16x32_bf16 v[112:115], v[182:185], v[190:193], v[112:115]
	v_mfma_f32_16x16x32_bf16 v[100:103], v[174:177], v[204:207], v[100:103]
	v_mfma_f32_16x16x32_bf16 v[96:99], v[182:185], v[204:207], v[96:99]
	v_mfma_f32_16x16x32_bf16 v[84:87], v[174:177], v[212:215], v[84:87]
	v_mfma_f32_16x16x32_bf16 v[80:83], v[182:185], v[212:215], v[80:83]
	v_mfma_f32_16x16x32_bf16 v[68:71], v[174:177], v[220:223], v[68:71]
	v_mfma_f32_16x16x32_bf16 v[64:67], v[182:185], v[220:223], v[64:67]
	v_mfma_f32_16x16x32_bf16 v[116:119], v[178:181], v[194:197], v[116:119]
	v_mfma_f32_16x16x32_bf16 v[112:115], v[186:189], v[194:197], v[112:115]
	v_mfma_f32_16x16x32_bf16 v[100:103], v[178:181], v[208:211], v[100:103]
	v_mfma_f32_16x16x32_bf16 v[96:99], v[186:189], v[208:211], v[96:99]
	v_mfma_f32_16x16x32_bf16 v[84:87], v[178:181], v[216:219], v[84:87]
	v_mfma_f32_16x16x32_bf16 v[80:83], v[186:189], v[216:219], v[80:83]
	v_mfma_f32_16x16x32_bf16 v[68:71], v[178:181], v[224:227], v[68:71]
	v_mfma_f32_16x16x32_bf16 v[64:67], v[186:189], v[224:227], v[64:67]
	s_setprio 0
	s_barrier
	s_add_i32 s45, s46, s26
	v_lshl_add_u64 v[144:145], s[22:23], 0, v[132:133]
	s_mov_b32 m0, s45
	ds_read_b128 v[190:193], v152 offset:16384
	ds_read_b128 v[194:197], v152 offset:17408
	ds_read_b128 v[204:207], v152 offset:18432
	ds_read_b128 v[208:211], v152 offset:19456
	ds_read_b128 v[212:215], v152 offset:20480
	ds_read_b128 v[216:219], v152 offset:21504
	ds_read_b128 v[220:223], v152 offset:22528
	ds_read_b128 v[224:227], v152 offset:23552
	global_load_lds_dwordx4 v[144:145], off
	s_add_i32 m0, s45, 0x2000
	s_add_u32 s48, s22, 0x40000
	v_lshl_add_u64 v[166:167], s[22:23], 0, v[128:129]
	s_addc_u32 s49, s23, 0
	s_add_i32 s45, s38, s26
	global_load_lds_dwordx4 v[166:167], off
	v_lshl_add_u64 v[228:229], s[48:49], 0, v[132:133]
	s_mov_b32 m0, s45
	v_lshl_add_u64 v[230:231], s[24:25], 0, v[130:131]
	global_load_lds_dwordx4 v[228:229], off
	v_lshl_add_u64 v[228:229], s[48:49], 0, v[128:129]
	s_add_i32 m0, s45, 0x2000
	s_nop 0
	global_load_lds_dwordx4 v[228:229], off
	v_lshl_add_u64 v[228:229], s[24:25], 0, v[134:135]
	s_mov_b32 m0, s21
	s_nop 0
	global_load_lds_dwordx4 v[228:229], off
	s_mov_b32 m0, s29
	s_nop 0
	global_load_lds_dwordx4 v[230:231], off
	s_waitcnt vmcnt(8)
	s_waitcnt lgkmcnt(0)
	s_barrier
; #define PG8_STAGE(bufoff, gbase, voff) do { _Pragma("unroll") for (int _i = 0; _i < 2; ++_i) \
;         __builtin_amdgcn_global_load_lds((const unsigned*)((const char*)(gbase) + (voff)[_i]), (PG8_LAS unsigned*)(lds + (bufoff) + ldsw + _i * 8192), 16, 0, 0); } while (0)
; #define PG8_LDA(dst, b, h) do { _Pragma("unroll") for (int m = 0; m < 4; ++m) _Pragma("unroll") for (int k = 0; k < 2; ++k) dst[m][k] = *(const PG8_LAS bf16x8*)(lds + PG8_SA(b, h) + aoff + m * 2048 + k * 1024); } while (0)
; #define PG8_LDB(dst, b, h) do { _Pragma("unroll") for (int n = 0; n < 2; ++n) _Pragma("unroll") for (int k = 0; k < 2; ++k) dst[n][k] = *(const PG8_LAS bf16x8*)(lds + PG8_SB(b, h) + boff + n * 2048 + k * 1024); } while (0)
; #define PG8_MMA(ai, bj, At, Bt) do { __builtin_amdgcn_s_setprio(1); _Pragma("unroll") for (int m = 0; m < 4; ++m) _Pragma("unroll") for (int n = 0; n < 2; ++n) _Pragma("unroll") for (int k = 0; k < 2; ++k) \
;         acc[ai][bj][m][n] = __builtin_amdgcn_mfma_f32_16x16x32_bf16(Bt[n][k], At[m][k], acc[ai][bj][m][n], 0, 0, 0); __builtin_amdgcn_s_setprio(0); } while (0)
; #define PG8_WAIT_V(n) asm volatile("s_waitcnt vmcnt(" #n ")" ::: "memory")
; #define PG8_WAIT_L(n) asm volatile("s_waitcnt lgkmcnt(" #n ")" ::: "memory")
; #define PG8_BAR __builtin_amdgcn_s_barrier()
; #define PG8_SCHED __builtin_amdgcn_sched_barrier(0)
; template <class Epi, class Sched, bool ALIGN_EPI = false, bool SP2 = false>
; __device__ __forceinline__ void gemm_phase(PG8_LAS unsigned char* lds, const Gemm g, const Sched& S, const Epi& E) {
;     ...
;             PG8_WAIT_V(8); PG8_WAIT_L(0); PG8_BAR; PG8_MMA(1, 0, At, B0); PG8_MMA(1, 1, At, B1); PG8_BAR; PG8_SCHED;
;             PG8_LDB(B0, 1, 0); PG8_LDB(B1, 1, 1); PG8_SCHED; PG8_LDA(At, 1, 0); PG8_STAGE(PG8_SA(0, 1), a2 + hstep, voffA);
;             PG8_WAIT_V(8); PG8_WAIT_L(0); PG8_BAR; PG8_MMA(0, 0, At, B0); PG8_MMA(0, 1, At, B1); PG8_BAR; PG8_SCHED;
	s_setprio 1
	s_waitcnt lgkmcnt(0)
	v_mfma_f32_16x16x32_bf16 v[60:63], v[154:157], v[190:193], v[60:63]
	v_mfma_f32_16x16x32_bf16 v[56:59], v[162:165], v[190:193], v[56:59]
	v_mfma_f32_16x16x32_bf16 v[44:47], v[154:157], v[204:207], v[44:47]
	v_mfma_f32_16x16x32_bf16 v[40:43], v[162:165], v[204:207], v[40:43]
	v_mfma_f32_16x16x32_bf16 v[28:31], v[154:157], v[212:215], v[28:31]
	v_mfma_f32_16x16x32_bf16 v[24:27], v[162:165], v[212:215], v[24:27]
	v_mfma_f32_16x16x32_bf16 v[12:15], v[154:157], v[220:223], v[12:15]
	v_mfma_f32_16x16x32_bf16 v[8:11], v[162:165], v[220:223], v[8:11]
	v_mfma_f32_16x16x32_bf16 v[60:63], v[158:161], v[194:197], v[60:63]
	v_mfma_f32_16x16x32_bf16 v[56:59], v[170:173], v[194:197], v[56:59]
	v_mfma_f32_16x16x32_bf16 v[44:47], v[158:161], v[208:211], v[44:47]
	v_mfma_f32_16x16x32_bf16 v[40:43], v[170:173], v[208:211], v[40:43]
	v_mfma_f32_16x16x32_bf16 v[28:31], v[158:161], v[216:219], v[28:31]
	v_mfma_f32_16x16x32_bf16 v[24:27], v[170:173], v[216:219], v[24:27]
	v_mfma_f32_16x16x32_bf16 v[12:15], v[158:161], v[224:227], v[12:15]
	v_mfma_f32_16x16x32_bf16 v[8:11], v[170:173], v[224:227], v[8:11]
	v_mfma_f32_16x16x32_bf16 v[52:55], v[174:177], v[190:193], v[52:55]
	v_mfma_f32_16x16x32_bf16 v[48:51], v[182:185], v[190:193], v[48:51]
	v_mfma_f32_16x16x32_bf16 v[36:39], v[174:177], v[204:207], v[36:39]
	v_mfma_f32_16x16x32_bf16 v[32:35], v[182:185], v[204:207], v[32:35]
	v_mfma_f32_16x16x32_bf16 v[20:23], v[174:177], v[212:215], v[20:23]
	v_mfma_f32_16x16x32_bf16 v[16:19], v[182:185], v[212:215], v[16:19]
	v_mfma_f32_16x16x32_bf16 v[4:7], v[174:177], v[220:223], v[4:7]
	v_mfma_f32_16x16x32_bf16 v[0:3], v[182:185], v[220:223], v[0:3]
	v_mfma_f32_16x16x32_bf16 v[52:55], v[178:181], v[194:197], v[52:55]
	v_mfma_f32_16x16x32_bf16 v[48:51], v[186:189], v[194:197], v[48:51]
	v_mfma_f32_16x16x32_bf16 v[36:39], v[178:181], v[208:211], v[36:39]
	v_mfma_f32_16x16x32_bf16 v[32:35], v[186:189], v[208:211], v[32:35]
	v_mfma_f32_16x16x32_bf16 v[20:23], v[178:181], v[216:219], v[20:23]
	v_mfma_f32_16x16x32_bf16 v[16:19], v[186:189], v[216:219], v[16:19]
	v_mfma_f32_16x16x32_bf16 v[4:7], v[178:181], v[224:227], v[4:7]
	v_mfma_f32_16x16x32_bf16 v[0:3], v[186:189], v[224:227], v[0:3]
	s_setprio 0
	s_barrier
	s_add_i32 s45, 0, 0x18000
	v_add_u32_e32 v153, s45, v147
	s_add_i32 s47, 0, 0x1c000
	ds_read_b128 v[154:157], v153
	ds_read_b128 v[158:161], v153 offset:1024
	ds_read_b128 v[162:165], v153 offset:2048
	ds_read_b128 v[170:173], v153 offset:3072
	v_add_u32_e32 v153, s47, v147
	ds_read_b128 v[174:177], v153
	ds_read_b128 v[178:181], v153 offset:1024
	ds_read_b128 v[182:185], v153 offset:2048
	ds_read_b128 v[186:189], v153 offset:3072
	s_add_u32 s24, s24, 0x40000
	s_addc_u32 s25, s25, 0
	s_mov_b32 m0, s30
	v_lshl_add_u64 v[232:233], s[24:25], 0, v[134:135]
	ds_read_b128 v[190:193], v152 offset:32768
	ds_read_b128 v[194:197], v152 offset:33792
	ds_read_b128 v[204:207], v152 offset:34816
	ds_read_b128 v[208:211], v152 offset:35840
	ds_read_b128 v[212:215], v152 offset:36864
	ds_read_b128 v[216:219], v152 offset:37888
	ds_read_b128 v[220:223], v152 offset:38912
	ds_read_b128 v[224:227], v152 offset:39936
	global_load_lds_dwordx4 v[232:233], off
	v_lshl_add_u64 v[232:233], s[24:25], 0, v[130:131]
	s_mov_b32 m0, s31
	s_nop 0
	global_load_lds_dwordx4 v[232:233], off
	s_waitcnt vmcnt(8)
	s_waitcnt lgkmcnt(0)
	s_barrier
	s_setprio 1
	s_waitcnt lgkmcnt(0)
	v_mfma_f32_16x16x32_bf16 v[124:127], v[154:157], v[190:193], v[124:127]
	v_mfma_f32_16x16x32_bf16 v[120:123], v[162:165], v[190:193], v[120:123]
	v_mfma_f32_16x16x32_bf16 v[108:111], v[154:157], v[204:207], v[108:111]
	v_mfma_f32_16x16x32_bf16 v[104:107], v[162:165], v[204:207], v[104:107]
	v_mfma_f32_16x16x32_bf16 v[92:95], v[154:157], v[212:215], v[92:95]
	v_mfma_f32_16x16x32_bf16 v[88:91], v[162:165], v[212:215], v[88:91]
	v_mfma_f32_16x16x32_bf16 v[76:79], v[154:157], v[220:223], v[76:79]
	v_mfma_f32_16x16x32_bf16 v[72:75], v[162:165], v[220:223], v[72:75]
	v_mfma_f32_16x16x32_bf16 v[124:127], v[158:161], v[194:197], v[124:127]
	v_mfma_f32_16x16x32_bf16 v[120:123], v[170:173], v[194:197], v[120:123]
	v_mfma_f32_16x16x32_bf16 v[108:111], v[158:161], v[208:211], v[108:111]
	v_mfma_f32_16x16x32_bf16 v[104:107], v[170:173], v[208:211], v[104:107]
	v_mfma_f32_16x16x32_bf16 v[92:95], v[158:161], v[216:219], v[92:95]
	v_mfma_f32_16x16x32_bf16 v[88:91], v[170:173], v[216:219], v[88:91]
	v_mfma_f32_16x16x32_bf16 v[76:79], v[158:161], v[224:227], v[76:79]
	v_mfma_f32_16x16x32_bf16 v[72:75], v[170:173], v[224:227], v[72:75]
	v_mfma_f32_16x16x32_bf16 v[116:119], v[174:177], v[190:193], v[116:119]
	v_mfma_f32_16x16x32_bf16 v[112:115], v[182:185], v[190:193], v[112:115]
	v_mfma_f32_16x16x32_bf16 v[100:103], v[174:177], v[204:207], v[100:103]
	v_mfma_f32_16x16x32_bf16 v[96:99], v[182:185], v[204:207], v[96:99]
	v_mfma_f32_16x16x32_bf16 v[84:87], v[174:177], v[212:215], v[84:87]
	v_mfma_f32_16x16x32_bf16 v[80:83], v[182:185], v[212:215], v[80:83]
	v_mfma_f32_16x16x32_bf16 v[68:71], v[174:177], v[220:223], v[68:71]
	v_mfma_f32_16x16x32_bf16 v[64:67], v[182:185], v[220:223], v[64:67]
	v_mfma_f32_16x16x32_bf16 v[116:119], v[178:181], v[194:197], v[116:119]
	v_mfma_f32_16x16x32_bf16 v[112:115], v[186:189], v[194:197], v[112:115]
	v_mfma_f32_16x16x32_bf16 v[100:103], v[178:181], v[208:211], v[100:103]
	v_mfma_f32_16x16x32_bf16 v[96:99], v[186:189], v[208:211], v[96:99]
	v_mfma_f32_16x16x32_bf16 v[84:87], v[178:181], v[216:219], v[84:87]
	v_mfma_f32_16x16x32_bf16 v[80:83], v[186:189], v[216:219], v[80:83]
	v_mfma_f32_16x16x32_bf16 v[68:71], v[178:181], v[224:227], v[68:71]
	v_mfma_f32_16x16x32_bf16 v[64:67], v[186:189], v[224:227], v[64:67]
	s_setprio 0
	s_barrier
; #define PG8_STAGE(bufoff, gbase, voff) do { _Pragma("unroll") for (int _i = 0; _i < 2; ++_i) \
;         __builtin_amdgcn_global_load_lds((const unsigned*)((const char*)(gbase) + (voff)[_i]), (PG8_LAS unsigned*)(lds + (bufoff) + ldsw + _i * 8192), 16, 0, 0); } while (0)
; #define PG8_LDA(dst, b, h) do { _Pragma("unroll") for (int m = 0; m < 4; ++m) _Pragma("unroll") for (int k = 0; k < 2; ++k) dst[m][k] = *(const PG8_LAS bf16x8*)(lds + PG8_SA(b, h) + aoff + m * 2048 + k * 1024); } while (0)
; #define PG8_MMA(ai, bj, At, Bt) do { __builtin_amdgcn_s_setprio(1); _Pragma("unroll") for (int m = 0; m < 4; ++m) _Pragma("unroll") for (int n = 0; n < 2; ++n) _Pragma("unroll") for (int k = 0; k < 2; ++k) \
;         acc[ai][bj][m][n] = __builtin_amdgcn_mfma_f32_16x16x32_bf16(Bt[n][k], At[m][k], acc[ai][bj][m][n], 0, 0, 0); __builtin_amdgcn_s_setprio(0); } while (0)
; #define PG8_WAIT_V(n) asm volatile("s_waitcnt vmcnt(" #n ")" ::: "memory")
; #define PG8_WAIT_L(n) asm volatile("s_waitcnt lgkmcnt(" #n ")" ::: "memory")
; #define PG8_BAR __builtin_amdgcn_s_barrier()
; #define PG8_SCHED __builtin_amdgcn_sched_barrier(0)
; template <class Epi, class Sched, bool ALIGN_EPI = false, bool SP2 = false>
; __device__ __forceinline__ void gemm_phase(PG8_LAS unsigned char* lds, const Gemm g, const Sched& S, const Epi& E) {
;     ...
;             PG8_LDA(At, 1, 1); PG8_STAGE(PG8_SB(1, 0), b3, voffB); PG8_STAGE(PG8_SB(1, 1), b3 + hstep, voffB); PG8_STAGE(PG8_SA(1, 0), a3, voffA);
;             PG8_WAIT_V(8); PG8_WAIT_L(0); PG8_BAR; PG8_MMA(1, 0, At, B0); PG8_MMA(1, 1, At, B1); PG8_BAR; PG8_SCHED;
	s_add_i32 s24, s45, s26
	v_lshl_add_u64 v[144:145], v[144:145], 0, s[8:9]
	s_mov_b32 m0, s24
	ds_read_b128 v[190:193], v152 offset:49152
	ds_read_b128 v[194:197], v152 offset:50176
	ds_read_b128 v[204:207], v152 offset:51200
	ds_read_b128 v[208:211], v152 offset:52224
	ds_read_b128 v[212:215], v152 offset:53248
	ds_read_b128 v[216:219], v152 offset:54272
	ds_read_b128 v[220:223], v152 offset:55296
	ds_read_b128 v[224:227], v152 offset:56320
	global_load_lds_dwordx4 v[144:145], off
	s_add_i32 m0, s24, 0x2000
	s_add_u32 s22, s22, 0x40080
	v_lshl_add_u64 v[144:145], v[166:167], 0, s[8:9]
	s_addc_u32 s23, s23, 0
	s_add_i32 s24, s47, s26
	global_load_lds_dwordx4 v[144:145], off
	v_lshl_add_u64 v[144:145], s[22:23], 0, v[132:133]
	s_mov_b32 m0, s24
	s_nop 0
	global_load_lds_dwordx4 v[144:145], off
	v_lshl_add_u64 v[144:145], s[22:23], 0, v[128:129]
	s_add_i32 m0, s24, 0x2000
	s_nop 0
	global_load_lds_dwordx4 v[144:145], off
	v_lshl_add_u64 v[144:145], v[228:229], 0, s[8:9]
	s_mov_b32 m0, s35
	s_nop 0
	global_load_lds_dwordx4 v[144:145], off
	v_lshl_add_u64 v[144:145], v[230:231], 0, s[8:9]
	s_mov_b32 m0, s36
	s_nop 0
	global_load_lds_dwordx4 v[144:145], off
	s_waitcnt vmcnt(8)
	s_waitcnt lgkmcnt(0)
	s_barrier
	s_setprio 1
	s_waitcnt lgkmcnt(0)
	v_mfma_f32_16x16x32_bf16 v[60:63], v[154:157], v[190:193], v[60:63]
	v_mfma_f32_16x16x32_bf16 v[56:59], v[162:165], v[190:193], v[56:59]
	v_mfma_f32_16x16x32_bf16 v[44:47], v[154:157], v[204:207], v[44:47]
	v_mfma_f32_16x16x32_bf16 v[40:43], v[162:165], v[204:207], v[40:43]
	v_mfma_f32_16x16x32_bf16 v[28:31], v[154:157], v[212:215], v[28:31]
	v_mfma_f32_16x16x32_bf16 v[24:27], v[162:165], v[212:215], v[24:27]
	v_mfma_f32_16x16x32_bf16 v[12:15], v[154:157], v[220:223], v[12:15]
	v_mfma_f32_16x16x32_bf16 v[8:11], v[162:165], v[220:223], v[8:11]
	v_mfma_f32_16x16x32_bf16 v[60:63], v[158:161], v[194:197], v[60:63]
	v_mfma_f32_16x16x32_bf16 v[56:59], v[170:173], v[194:197], v[56:59]
	v_mfma_f32_16x16x32_bf16 v[44:47], v[158:161], v[208:211], v[44:47]
	v_mfma_f32_16x16x32_bf16 v[40:43], v[170:173], v[208:211], v[40:43]
	v_mfma_f32_16x16x32_bf16 v[28:31], v[158:161], v[216:219], v[28:31]
	v_mfma_f32_16x16x32_bf16 v[24:27], v[170:173], v[216:219], v[24:27]
	v_mfma_f32_16x16x32_bf16 v[12:15], v[158:161], v[224:227], v[12:15]
	v_mfma_f32_16x16x32_bf16 v[8:11], v[170:173], v[224:227], v[8:11]
	v_mfma_f32_16x16x32_bf16 v[52:55], v[174:177], v[190:193], v[52:55]
	v_mfma_f32_16x16x32_bf16 v[48:51], v[182:185], v[190:193], v[48:51]
	v_mfma_f32_16x16x32_bf16 v[36:39], v[174:177], v[204:207], v[36:39]
	v_mfma_f32_16x16x32_bf16 v[32:35], v[182:185], v[204:207], v[32:35]
	v_mfma_f32_16x16x32_bf16 v[20:23], v[174:177], v[212:215], v[20:23]
	v_mfma_f32_16x16x32_bf16 v[16:19], v[182:185], v[212:215], v[16:19]
	v_mfma_f32_16x16x32_bf16 v[4:7], v[174:177], v[220:223], v[4:7]
	v_mfma_f32_16x16x32_bf16 v[0:3], v[182:185], v[220:223], v[0:3]
	v_mfma_f32_16x16x32_bf16 v[52:55], v[178:181], v[194:197], v[52:55]
	v_mfma_f32_16x16x32_bf16 v[48:51], v[186:189], v[194:197], v[48:51]
	v_mfma_f32_16x16x32_bf16 v[36:39], v[178:181], v[208:211], v[36:39]
	v_mfma_f32_16x16x32_bf16 v[32:35], v[186:189], v[208:211], v[32:35]
	v_mfma_f32_16x16x32_bf16 v[20:23], v[178:181], v[216:219], v[20:23]
	v_mfma_f32_16x16x32_bf16 v[16:19], v[186:189], v[216:219], v[16:19]
	v_mfma_f32_16x16x32_bf16 v[4:7], v[178:181], v[224:227], v[4:7]
	v_mfma_f32_16x16x32_bf16 v[0:3], v[186:189], v[224:227], v[0:3]
	s_setprio 0
	s_barrier
	s_add_i32 s44, s44, 2
	s_add_u32 s0, s0, 0x100
	s_addc_u32 s1, s1, 0
	s_add_u32 s42, s42, 0x100
	s_addc_u32 s43, s43, 0
	s_cmp_gt_u32 s44, 13
	s_cbranch_scc0 .LBB0_826
	s_and_b64 vcc, exec, s[10:11]
	s_cbranch_vccz .LBB0_829
	s_barrier

; #define PG8_STAGE(bufoff, gbase, voff) do { _Pragma("unroll") for (int _i = 0; _i < 2; ++_i) \
;         __builtin_amdgcn_global_load_lds((const unsigned*)((const char*)(gbase) + (voff)[_i]), (PG8_LAS unsigned*)(lds + (bufoff) + ldsw + _i * 8192), 16, 0, 0); } while (0)
; #define PG8_LDA(dst, b, h) do { _Pragma("unroll") for (int m = 0; m < 4; ++m) _Pragma("unroll") for (int k = 0; k < 2; ++k) dst[m][k] = *(const PG8_LAS bf16x8*)(lds + PG8_SA(b, h) + aoff + m * 2048 + k * 1024); } while (0)
; #define PG8_LDB(dst, b, h) do { _Pragma("unroll") for (int n = 0; n < 2; ++n) _Pragma("unroll") for (int k = 0; k < 2; ++k) dst[n][k] = *(const PG8_LAS bf16x8*)(lds + PG8_SB(b, h) + boff + n * 2048 + k * 1024); } while (0)
; #define PG8_MMA(ai, bj, At, Bt) do { __builtin_amdgcn_s_setprio(1); _Pragma("unroll") for (int m = 0; m < 4; ++m) _Pragma("unroll") for (int n = 0; n < 2; ++n) _Pragma("unroll") for (int k = 0; k < 2; ++k) \
;         acc[ai][bj][m][n] = __builtin_amdgcn_mfma_f32_16x16x32_bf16(Bt[n][k], At[m][k], acc[ai][bj][m][n], 0, 0, 0); __builtin_amdgcn_s_setprio(0); } while (0)
; #define PG8_WAIT_V(n) asm volatile("s_waitcnt vmcnt(" #n ")" ::: "memory")
; #define PG8_WAIT_L(n) asm volatile("s_waitcnt lgkmcnt(" #n ")" ::: "memory")
; #define PG8_BAR __builtin_amdgcn_s_barrier()
; #define PG8_SCHED __builtin_amdgcn_sched_barrier(0)
; template <class Epi, class Sched, bool ALIGN_EPI = false, bool SP2 = false>
; __device__ __forceinline__ void gemm_phase(PG8_LAS unsigned char* lds, const Gemm g, const Sched& S, const Epi& E) {
;     ...
;             const bool last = (t == nt - 2);
;             const char* a1 = cA + (size_t)(t + 1) * kstep;
;             const char* a2 = last ? nA : cA + (size_t)(t + 2) * kstep; const char* b2 = last ? nB : cB + (size_t)(t + 2) * kstep;
;             const char* a3 = a2 + kstep; const char* b3 = b2 + kstep;
;             if (last && has_next) S.a_ready(nxt);
;             if constexpr (SP2) {
;             PG8_LDB(B0, 0, 0); PG8_LDB(B1, 0, 1); PG8_SCHED; PG8_LDA(At, 0, 0); PG8_STAGE(PG8_SA(1, 1), a1 + hstep, voffA);
;             PG8_WAIT_V(8); PG8_WAIT_L(0); PG8_BAR; PG8_MMA(0, 0, At, B0); PG8_MMA(0, 1, At, B1); PG8_BAR; PG8_SCHED;
;             PG8_LDA(At, 0, 1); PG8_STAGE(PG8_SB(0, 0), b2, voffB); PG8_STAGE(PG8_SB(0, 1), b2 + hstep, voffB); PG8_STAGE(PG8_SA(0, 0), a2, voffA);
.LBB0_908:
	ds_read_b128 v[128:131], v189
	ds_read_b128 v[132:135], v189 offset:1024
	ds_read_b128 v[136:139], v189 offset:2048
	ds_read_b128 v[140:143], v189 offset:3072
	ds_read_b128 v[144:147], v190
	ds_read_b128 v[148:151], v190 offset:1024
	ds_read_b128 v[152:155], v190 offset:2048
	ds_read_b128 v[156:159], v190 offset:3072
	s_add_u32 s24, s22, 0x100
	s_addc_u32 s25, s23, 0
	s_cmp_eq_u32 s65, 40
	s_cselect_b32 s29, s9, s25
	s_cselect_b32 s28, s8, s24
	s_cselect_b32 s27, s21, s63
	s_cselect_b32 s26, s20, s62
	v_lshl_add_u64 v[182:183], s[22:23], 0, v[170:171]
	s_add_i32 m0, s31, 0xc000
	ds_read_b128 v[178:181], v191
	ds_read_b128 v[196:199], v191 offset:1024
	ds_read_b128 v[204:207], v191 offset:2048
	ds_read_b128 v[208:211], v191 offset:3072
	ds_read_b128 v[212:215], v191 offset:4096
	ds_read_b128 v[216:219], v191 offset:5120
	ds_read_b128 v[220:223], v191 offset:6144
	ds_read_b128 v[224:227], v191 offset:7168
	global_load_lds_dwordx4 v[182:183], off
	v_lshl_add_u64 v[182:183], s[22:23], 0, v[172:173]
	s_add_i32 m0, s31, 0xe000
	s_nop 0
	global_load_lds_dwordx4 v[182:183], off
	s_waitcnt vmcnt(8)
	s_waitcnt lgkmcnt(0)
	s_barrier
	s_setprio 1
	s_waitcnt lgkmcnt(0)
	v_mfma_f32_16x16x32_bf16 v[124:127], v[128:131], v[178:181], v[124:127]
	v_mfma_f32_16x16x32_bf16 v[120:123], v[136:139], v[178:181], v[120:123]
	v_mfma_f32_16x16x32_bf16 v[108:111], v[128:131], v[204:207], v[108:111]
	v_mfma_f32_16x16x32_bf16 v[104:107], v[136:139], v[204:207], v[104:107]
	v_mfma_f32_16x16x32_bf16 v[92:95], v[128:131], v[212:215], v[92:95]
	v_mfma_f32_16x16x32_bf16 v[88:91], v[136:139], v[212:215], v[88:91]
	v_mfma_f32_16x16x32_bf16 v[76:79], v[128:131], v[220:223], v[76:79]
	v_mfma_f32_16x16x32_bf16 v[72:75], v[136:139], v[220:223], v[72:75]
	v_mfma_f32_16x16x32_bf16 v[124:127], v[132:135], v[196:199], v[124:127]
	v_mfma_f32_16x16x32_bf16 v[120:123], v[140:143], v[196:199], v[120:123]
	v_mfma_f32_16x16x32_bf16 v[108:111], v[132:135], v[208:211], v[108:111]
	v_mfma_f32_16x16x32_bf16 v[104:107], v[140:143], v[208:211], v[104:107]
	v_mfma_f32_16x16x32_bf16 v[92:95], v[132:135], v[216:219], v[92:95]
	v_mfma_f32_16x16x32_bf16 v[88:91], v[140:143], v[216:219], v[88:91]
	v_mfma_f32_16x16x32_bf16 v[76:79], v[132:135], v[224:227], v[76:79]
	v_mfma_f32_16x16x32_bf16 v[72:75], v[140:143], v[224:227], v[72:75]
	v_mfma_f32_16x16x32_bf16 v[116:119], v[144:147], v[178:181], v[116:119]
	v_mfma_f32_16x16x32_bf16 v[112:115], v[152:155], v[178:181], v[112:115]
	v_mfma_f32_16x16x32_bf16 v[100:103], v[144:147], v[204:207], v[100:103]
	v_mfma_f32_16x16x32_bf16 v[96:99], v[152:155], v[204:207], v[96:99]
	v_mfma_f32_16x16x32_bf16 v[84:87], v[144:147], v[212:215], v[84:87]
	v_mfma_f32_16x16x32_bf16 v[80:83], v[152:155], v[212:215], v[80:83]
	v_mfma_f32_16x16x32_bf16 v[68:71], v[144:147], v[220:223], v[68:71]
	v_mfma_f32_16x16x32_bf16 v[64:67], v[152:155], v[220:223], v[64:67]
	v_mfma_f32_16x16x32_bf16 v[116:119], v[148:151], v[196:199], v[116:119]
	v_mfma_f32_16x16x32_bf16 v[112:115], v[156:159], v[196:199], v[112:115]
	v_mfma_f32_16x16x32_bf16 v[100:103], v[148:151], v[208:211], v[100:103]
	v_mfma_f32_16x16x32_bf16 v[96:99], v[156:159], v[208:211], v[96:99]
	v_mfma_f32_16x16x32_bf16 v[84:87], v[148:151], v[216:219], v[84:87]
	v_mfma_f32_16x16x32_bf16 v[80:83], v[156:159], v[216:219], v[80:83]
	v_mfma_f32_16x16x32_bf16 v[68:71], v[148:151], v[224:227], v[68:71]
	v_mfma_f32_16x16x32_bf16 v[64:67], v[156:159], v[224:227], v[64:67]
	s_setprio 0
	s_barrier
	s_add_i32 s22, s46, s30
	v_lshl_add_u64 v[182:183], s[26:27], 0, v[162:163]
	s_mov_b32 m0, s22
	ds_read_b128 v[178:181], v191 offset:16384
	ds_read_b128 v[196:199], v191 offset:17408
	ds_read_b128 v[204:207], v191 offset:18432
	ds_read_b128 v[208:211], v191 offset:19456
	ds_read_b128 v[212:215], v191 offset:20480
	ds_read_b128 v[216:219], v191 offset:21504
	ds_read_b128 v[220:223], v191 offset:22528
	ds_read_b128 v[224:227], v191 offset:23552
	global_load_lds_dwordx4 v[182:183], off
	s_add_i32 m0, s22, 0x2000
	s_add_u32 s22, s26, 0xb0000
	v_lshl_add_u64 v[200:201], s[26:27], 0, v[166:167]
	s_addc_u32 s23, s27, 0
	s_add_i32 s66, s47, s30
	global_load_lds_dwordx4 v[200:201], off
	v_lshl_add_u64 v[228:229], s[22:23], 0, v[162:163]
	s_mov_b32 m0, s66
	v_lshl_add_u64 v[230:231], s[28:29], 0, v[164:165]
	global_load_lds_dwordx4 v[228:229], off
	v_lshl_add_u64 v[228:229], s[22:23], 0, v[166:167]
	s_add_i32 m0, s66, 0x2000
	s_nop 0
	global_load_lds_dwordx4 v[228:229], off
	v_lshl_add_u64 v[228:229], s[28:29], 0, v[160:161]
	s_mov_b32 m0, s31
	s_nop 0
	global_load_lds_dwordx4 v[228:229], off
	s_mov_b32 m0, s33
	s_nop 0
	global_load_lds_dwordx4 v[230:231], off
	s_waitcnt vmcnt(8)
	s_waitcnt lgkmcnt(0)
	s_barrier
; #define PG8_STAGE(bufoff, gbase, voff) do { _Pragma("unroll") for (int _i = 0; _i < 2; ++_i) \
;         __builtin_amdgcn_global_load_lds((const unsigned*)((const char*)(gbase) + (voff)[_i]), (PG8_LAS unsigned*)(lds + (bufoff) + ldsw + _i * 8192), 16, 0, 0); } while (0)
; #define PG8_LDA(dst, b, h) do { _Pragma("unroll") for (int m = 0; m < 4; ++m) _Pragma("unroll") for (int k = 0; k < 2; ++k) dst[m][k] = *(const PG8_LAS bf16x8*)(lds + PG8_SA(b, h) + aoff + m * 2048 + k * 1024); } while (0)
; #define PG8_LDB(dst, b, h) do { _Pragma("unroll") for (int n = 0; n < 2; ++n) _Pragma("unroll") for (int k = 0; k < 2; ++k) dst[n][k] = *(const PG8_LAS bf16x8*)(lds + PG8_SB(b, h) + boff + n * 2048 + k * 1024); } while (0)
; #define PG8_MMA(ai, bj, At, Bt) do { __builtin_amdgcn_s_setprio(1); _Pragma("unroll") for (int m = 0; m < 4; ++m) _Pragma("unroll") for (int n = 0; n < 2; ++n) _Pragma("unroll") for (int k = 0; k < 2; ++k) \
;         acc[ai][bj][m][n] = __builtin_amdgcn_mfma_f32_16x16x32_bf16(Bt[n][k], At[m][k], acc[ai][bj][m][n], 0, 0, 0); __builtin_amdgcn_s_setprio(0); } while (0)
; #define PG8_WAIT_V(n) asm volatile("s_waitcnt vmcnt(" #n ")" ::: "memory")
; #define PG8_WAIT_L(n) asm volatile("s_waitcnt lgkmcnt(" #n ")" ::: "memory")
; #define PG8_BAR __builtin_amdgcn_s_barrier()
; #define PG8_SCHED __builtin_amdgcn_sched_barrier(0)
; template <class Epi, class Sched, bool ALIGN_EPI = false, bool SP2 = false>
; __device__ __forceinline__ void gemm_phase(PG8_LAS unsigned char* lds, const Gemm g, const Sched& S, const Epi& E) {
;     ...
;             PG8_WAIT_V(8); PG8_WAIT_L(0); PG8_BAR; PG8_MMA(1, 0, At, B0); PG8_MMA(1, 1, At, B1); PG8_BAR; PG8_SCHED;
;             PG8_LDB(B0, 1, 0); PG8_LDB(B1, 1, 1); PG8_SCHED; PG8_LDA(At, 1, 0); PG8_STAGE(PG8_SA(0, 1), a2 + hstep, voffA);
;             PG8_WAIT_V(8); PG8_WAIT_L(0); PG8_BAR; PG8_MMA(0, 0, At, B0); PG8_MMA(0, 1, At, B1); PG8_BAR; PG8_SCHED;
	s_setprio 1
	s_waitcnt lgkmcnt(0)
	v_mfma_f32_16x16x32_bf16 v[60:63], v[128:131], v[178:181], v[60:63]
	v_mfma_f32_16x16x32_bf16 v[56:59], v[136:139], v[178:181], v[56:59]
	v_mfma_f32_16x16x32_bf16 v[44:47], v[128:131], v[204:207], v[44:47]
	v_mfma_f32_16x16x32_bf16 v[40:43], v[136:139], v[204:207], v[40:43]
	v_mfma_f32_16x16x32_bf16 v[28:31], v[128:131], v[212:215], v[28:31]
	v_mfma_f32_16x16x32_bf16 v[24:27], v[136:139], v[212:215], v[24:27]
	v_mfma_f32_16x16x32_bf16 v[12:15], v[128:131], v[220:223], v[12:15]
	v_mfma_f32_16x16x32_bf16 v[8:11], v[136:139], v[220:223], v[8:11]
	v_mfma_f32_16x16x32_bf16 v[60:63], v[132:135], v[196:199], v[60:63]
	v_mfma_f32_16x16x32_bf16 v[56:59], v[140:143], v[196:199], v[56:59]
	v_mfma_f32_16x16x32_bf16 v[44:47], v[132:135], v[208:211], v[44:47]
	v_mfma_f32_16x16x32_bf16 v[40:43], v[140:143], v[208:211], v[40:43]
	v_mfma_f32_16x16x32_bf16 v[28:31], v[132:135], v[216:219], v[28:31]
	v_mfma_f32_16x16x32_bf16 v[24:27], v[140:143], v[216:219], v[24:27]
	v_mfma_f32_16x16x32_bf16 v[12:15], v[132:135], v[224:227], v[12:15]
	v_mfma_f32_16x16x32_bf16 v[8:11], v[140:143], v[224:227], v[8:11]
	v_mfma_f32_16x16x32_bf16 v[52:55], v[144:147], v[178:181], v[52:55]
	v_mfma_f32_16x16x32_bf16 v[48:51], v[152:155], v[178:181], v[48:51]
	v_mfma_f32_16x16x32_bf16 v[36:39], v[144:147], v[204:207], v[36:39]
	v_mfma_f32_16x16x32_bf16 v[32:35], v[152:155], v[204:207], v[32:35]
	v_mfma_f32_16x16x32_bf16 v[20:23], v[144:147], v[212:215], v[20:23]
	v_mfma_f32_16x16x32_bf16 v[16:19], v[152:155], v[212:215], v[16:19]
	v_mfma_f32_16x16x32_bf16 v[4:7], v[144:147], v[220:223], v[4:7]
	v_mfma_f32_16x16x32_bf16 v[0:3], v[152:155], v[220:223], v[0:3]
	v_mfma_f32_16x16x32_bf16 v[52:55], v[148:151], v[196:199], v[52:55]
	v_mfma_f32_16x16x32_bf16 v[48:51], v[156:159], v[196:199], v[48:51]
	v_mfma_f32_16x16x32_bf16 v[36:39], v[148:151], v[208:211], v[36:39]
	v_mfma_f32_16x16x32_bf16 v[32:35], v[156:159], v[208:211], v[32:35]
	v_mfma_f32_16x16x32_bf16 v[20:23], v[148:151], v[216:219], v[20:23]
	v_mfma_f32_16x16x32_bf16 v[16:19], v[156:159], v[216:219], v[16:19]
	v_mfma_f32_16x16x32_bf16 v[4:7], v[148:151], v[224:227], v[4:7]
	v_mfma_f32_16x16x32_bf16 v[0:3], v[156:159], v[224:227], v[0:3]
	s_setprio 0
	s_barrier
	s_add_i32 s66, 0, 0x18000
	s_add_i32 s67, 0, 0x1c000
	v_add_u32_e32 v140, s66, v185
	v_add_u32_e32 v156, s67, v185
	ds_read_b128 v[128:131], v140
	ds_read_b128 v[132:135], v140 offset:1024
	ds_read_b128 v[136:139], v140 offset:2048
	ds_read_b128 v[140:143], v140 offset:3072
	ds_read_b128 v[144:147], v156
	ds_read_b128 v[148:151], v156 offset:1024
	ds_read_b128 v[152:155], v156 offset:2048
	ds_read_b128 v[156:159], v156 offset:3072
	s_add_u32 s22, s28, 0xb0000
	s_addc_u32 s23, s29, 0
	s_mov_b32 m0, s34
	v_lshl_add_u64 v[232:233], s[22:23], 0, v[160:161]
	ds_read_b128 v[178:181], v191 offset:32768
	ds_read_b128 v[196:199], v191 offset:33792
	ds_read_b128 v[204:207], v191 offset:34816
	ds_read_b128 v[208:211], v191 offset:35840
	ds_read_b128 v[212:215], v191 offset:36864
	ds_read_b128 v[216:219], v191 offset:37888
	ds_read_b128 v[220:223], v191 offset:38912
	ds_read_b128 v[224:227], v191 offset:39936
	global_load_lds_dwordx4 v[232:233], off
	v_lshl_add_u64 v[232:233], s[22:23], 0, v[164:165]
	s_mov_b32 m0, s35
	s_nop 0
	global_load_lds_dwordx4 v[232:233], off
	s_waitcnt vmcnt(8)
	s_waitcnt lgkmcnt(0)
	s_barrier
	s_setprio 1
	s_waitcnt lgkmcnt(0)
	v_mfma_f32_16x16x32_bf16 v[124:127], v[128:131], v[178:181], v[124:127]
	v_mfma_f32_16x16x32_bf16 v[120:123], v[136:139], v[178:181], v[120:123]
	v_mfma_f32_16x16x32_bf16 v[108:111], v[128:131], v[204:207], v[108:111]
	v_mfma_f32_16x16x32_bf16 v[104:107], v[136:139], v[204:207], v[104:107]
	v_mfma_f32_16x16x32_bf16 v[92:95], v[128:131], v[212:215], v[92:95]
	v_mfma_f32_16x16x32_bf16 v[88:91], v[136:139], v[212:215], v[88:91]
	v_mfma_f32_16x16x32_bf16 v[76:79], v[128:131], v[220:223], v[76:79]
	v_mfma_f32_16x16x32_bf16 v[72:75], v[136:139], v[220:223], v[72:75]
	v_mfma_f32_16x16x32_bf16 v[124:127], v[132:135], v[196:199], v[124:127]
	v_mfma_f32_16x16x32_bf16 v[120:123], v[140:143], v[196:199], v[120:123]
	v_mfma_f32_16x16x32_bf16 v[108:111], v[132:135], v[208:211], v[108:111]
	v_mfma_f32_16x16x32_bf16 v[104:107], v[140:143], v[208:211], v[104:107]
	v_mfma_f32_16x16x32_bf16 v[92:95], v[132:135], v[216:219], v[92:95]
	v_mfma_f32_16x16x32_bf16 v[88:91], v[140:143], v[216:219], v[88:91]
	v_mfma_f32_16x16x32_bf16 v[76:79], v[132:135], v[224:227], v[76:79]
	v_mfma_f32_16x16x32_bf16 v[72:75], v[140:143], v[224:227], v[72:75]
	v_mfma_f32_16x16x32_bf16 v[116:119], v[144:147], v[178:181], v[116:119]
	v_mfma_f32_16x16x32_bf16 v[112:115], v[152:155], v[178:181], v[112:115]
	v_mfma_f32_16x16x32_bf16 v[100:103], v[144:147], v[204:207], v[100:103]
	v_mfma_f32_16x16x32_bf16 v[96:99], v[152:155], v[204:207], v[96:99]
	v_mfma_f32_16x16x32_bf16 v[84:87], v[144:147], v[212:215], v[84:87]
	v_mfma_f32_16x16x32_bf16 v[80:83], v[152:155], v[212:215], v[80:83]
	v_mfma_f32_16x16x32_bf16 v[68:71], v[144:147], v[220:223], v[68:71]
	v_mfma_f32_16x16x32_bf16 v[64:67], v[152:155], v[220:223], v[64:67]
	v_mfma_f32_16x16x32_bf16 v[116:119], v[148:151], v[196:199], v[116:119]
	v_mfma_f32_16x16x32_bf16 v[112:115], v[156:159], v[196:199], v[112:115]
	v_mfma_f32_16x16x32_bf16 v[100:103], v[148:151], v[208:211], v[100:103]
	v_mfma_f32_16x16x32_bf16 v[96:99], v[156:159], v[208:211], v[96:99]
	v_mfma_f32_16x16x32_bf16 v[84:87], v[148:151], v[216:219], v[84:87]
	v_mfma_f32_16x16x32_bf16 v[80:83], v[156:159], v[216:219], v[80:83]
	v_mfma_f32_16x16x32_bf16 v[68:71], v[148:151], v[224:227], v[68:71]
	v_mfma_f32_16x16x32_bf16 v[64:67], v[156:159], v[224:227], v[64:67]
	s_setprio 0
	s_barrier
; #define PG8_STAGE(bufoff, gbase, voff) do { _Pragma("unroll") for (int _i = 0; _i < 2; ++_i) \
;         __builtin_amdgcn_global_load_lds((const unsigned*)((const char*)(gbase) + (voff)[_i]), (PG8_LAS unsigned*)(lds + (bufoff) + ldsw + _i * 8192), 16, 0, 0); } while (0)
; #define PG8_LDA(dst, b, h) do { _Pragma("unroll") for (int m = 0; m < 4; ++m) _Pragma("unroll") for (int k = 0; k < 2; ++k) dst[m][k] = *(const PG8_LAS bf16x8*)(lds + PG8_SA(b, h) + aoff + m * 2048 + k * 1024); } while (0)
; #define PG8_MMA(ai, bj, At, Bt) do { __builtin_amdgcn_s_setprio(1); _Pragma("unroll") for (int m = 0; m < 4; ++m) _Pragma("unroll") for (int n = 0; n < 2; ++n) _Pragma("unroll") for (int k = 0; k < 2; ++k) \
;         acc[ai][bj][m][n] = __builtin_amdgcn_mfma_f32_16x16x32_bf16(Bt[n][k], At[m][k], acc[ai][bj][m][n], 0, 0, 0); __builtin_amdgcn_s_setprio(0); } while (0)
; #define PG8_WAIT_V(n) asm volatile("s_waitcnt vmcnt(" #n ")" ::: "memory")
; #define PG8_WAIT_L(n) asm volatile("s_waitcnt lgkmcnt(" #n ")" ::: "memory")
; #define PG8_BAR __builtin_amdgcn_s_barrier()
; #define PG8_SCHED __builtin_amdgcn_sched_barrier(0)
; template <class Epi, class Sched, bool ALIGN_EPI = false, bool SP2 = false>
; __device__ __forceinline__ void gemm_phase(PG8_LAS unsigned char* lds, const Gemm g, const Sched& S, const Epi& E) {
;     ...
;             PG8_LDA(At, 1, 1); PG8_STAGE(PG8_SB(1, 0), b3, voffB); PG8_STAGE(PG8_SB(1, 1), b3 + hstep, voffB); PG8_STAGE(PG8_SA(1, 0), a3, voffA);
;             PG8_WAIT_V(8); PG8_WAIT_L(0); PG8_BAR; PG8_MMA(1, 0, At, B0); PG8_MMA(1, 1, At, B1); PG8_BAR; PG8_SCHED;
	s_add_i32 s22, s66, s30
	v_lshl_add_u64 v[182:183], v[182:183], 0, s[14:15]
	s_mov_b32 m0, s22
	ds_read_b128 v[178:181], v191 offset:49152
	ds_read_b128 v[196:199], v191 offset:50176
	ds_read_b128 v[204:207], v191 offset:51200
	ds_read_b128 v[208:211], v191 offset:52224
	ds_read_b128 v[212:215], v191 offset:53248
	ds_read_b128 v[216:219], v191 offset:54272
	ds_read_b128 v[220:223], v191 offset:55296
	ds_read_b128 v[224:227], v191 offset:56320
	global_load_lds_dwordx4 v[182:183], off
	s_add_i32 m0, s22, 0x2000
	s_add_u32 s22, s26, 0xb0080
	v_lshl_add_u64 v[182:183], v[200:201], 0, s[14:15]
	s_addc_u32 s23, s27, 0
	s_add_i32 s26, s67, s30
	global_load_lds_dwordx4 v[182:183], off
	v_lshl_add_u64 v[182:183], s[22:23], 0, v[162:163]
	s_mov_b32 m0, s26
	s_nop 0
	global_load_lds_dwordx4 v[182:183], off
	v_lshl_add_u64 v[182:183], s[22:23], 0, v[166:167]
	s_add_i32 m0, s26, 0x2000
	s_nop 0
	global_load_lds_dwordx4 v[182:183], off
	v_lshl_add_u64 v[182:183], v[228:229], 0, s[14:15]
	s_mov_b32 m0, s40
	s_nop 0
	global_load_lds_dwordx4 v[182:183], off
	v_lshl_add_u64 v[182:183], v[230:231], 0, s[14:15]
	s_mov_b32 m0, s41
	s_nop 0
	global_load_lds_dwordx4 v[182:183], off
	s_waitcnt vmcnt(8)
	s_waitcnt lgkmcnt(0)
	s_barrier
	s_setprio 1
	s_waitcnt lgkmcnt(0)
	v_mfma_f32_16x16x32_bf16 v[60:63], v[128:131], v[178:181], v[60:63]
	v_mfma_f32_16x16x32_bf16 v[56:59], v[136:139], v[178:181], v[56:59]
	v_mfma_f32_16x16x32_bf16 v[44:47], v[128:131], v[204:207], v[44:47]
	v_mfma_f32_16x16x32_bf16 v[40:43], v[136:139], v[204:207], v[40:43]
	v_mfma_f32_16x16x32_bf16 v[28:31], v[128:131], v[212:215], v[28:31]
	v_mfma_f32_16x16x32_bf16 v[24:27], v[136:139], v[212:215], v[24:27]
	v_mfma_f32_16x16x32_bf16 v[12:15], v[128:131], v[220:223], v[12:15]
	v_mfma_f32_16x16x32_bf16 v[8:11], v[136:139], v[220:223], v[8:11]
	v_mfma_f32_16x16x32_bf16 v[60:63], v[132:135], v[196:199], v[60:63]
	v_mfma_f32_16x16x32_bf16 v[56:59], v[140:143], v[196:199], v[56:59]
	v_mfma_f32_16x16x32_bf16 v[44:47], v[132:135], v[208:211], v[44:47]
	v_mfma_f32_16x16x32_bf16 v[40:43], v[140:143], v[208:211], v[40:43]
	v_mfma_f32_16x16x32_bf16 v[28:31], v[132:135], v[216:219], v[28:31]
	v_mfma_f32_16x16x32_bf16 v[24:27], v[140:143], v[216:219], v[24:27]
	v_mfma_f32_16x16x32_bf16 v[12:15], v[132:135], v[224:227], v[12:15]
	v_mfma_f32_16x16x32_bf16 v[8:11], v[140:143], v[224:227], v[8:11]
	v_mfma_f32_16x16x32_bf16 v[52:55], v[144:147], v[178:181], v[52:55]
	v_mfma_f32_16x16x32_bf16 v[48:51], v[152:155], v[178:181], v[48:51]
	v_mfma_f32_16x16x32_bf16 v[36:39], v[144:147], v[204:207], v[36:39]
	v_mfma_f32_16x16x32_bf16 v[32:35], v[152:155], v[204:207], v[32:35]
	v_mfma_f32_16x16x32_bf16 v[20:23], v[144:147], v[212:215], v[20:23]
	v_mfma_f32_16x16x32_bf16 v[16:19], v[152:155], v[212:215], v[16:19]
	v_mfma_f32_16x16x32_bf16 v[4:7], v[144:147], v[220:223], v[4:7]
	v_mfma_f32_16x16x32_bf16 v[0:3], v[152:155], v[220:223], v[0:3]
	v_mfma_f32_16x16x32_bf16 v[52:55], v[148:151], v[196:199], v[52:55]
	v_mfma_f32_16x16x32_bf16 v[48:51], v[156:159], v[196:199], v[48:51]
	v_mfma_f32_16x16x32_bf16 v[36:39], v[148:151], v[208:211], v[36:39]
	v_mfma_f32_16x16x32_bf16 v[32:35], v[156:159], v[208:211], v[32:35]
	v_mfma_f32_16x16x32_bf16 v[20:23], v[148:151], v[216:219], v[20:23]
	v_mfma_f32_16x16x32_bf16 v[16:19], v[156:159], v[216:219], v[16:19]
	v_mfma_f32_16x16x32_bf16 v[4:7], v[148:151], v[224:227], v[4:7]
	v_mfma_f32_16x16x32_bf16 v[0:3], v[156:159], v[224:227], v[0:3]
	s_setprio 0
	s_barrier
	s_add_i32 s65, s65, 2
	s_add_u32 s62, s62, 0x100
	s_addc_u32 s63, s63, 0
	s_cmp_gt_u32 s65, 41
	s_mov_b64 s[22:23], s[24:25]
	s_cbranch_scc0 .LBB0_908
	s_and_b64 vcc, exec, s[16:17]
	s_cbranch_vccz .LBB0_911
	s_barrier
